# PEER gather table loads marked sc1 (agent scope: L1 bypass, lines are used once per CU)
# baseline (speedup 1.0000x reference)
; DEV float bflo(unsigned u) { return __uint_as_float(u << 16); }
; DEV float bfhi(unsigned u) { return __uint_as_float(u & 0xffff0000u); }
; DEV int tid_l() { int t = threadIdx.x; asm volatile("" : "+v"(t)); return t; }
; #define PG_ISSUE(BUF, TAB, e0_) do { const int isrc_ = ((e0_) < 64) ? myi0 : myi1; \
;       _Pragma("unroll") for (int e = 0; e < 8; ++e) { const int idx_ = __builtin_amdgcn_readlane(isrc_, ((e0_) + e) & 63); \
;         BUF[e] = *(const u32x4*)((TAB) + (size_t)idx_ * 1024 + lane * 16); } } while (0)
; DEV void peer_gather(const Params& P, int l, int m0, const int* idxs, const float* gs) {
;   const int tid = tid_l(), lane = tid & 63, wid = tid >> 6;
;   const unsigned char* U = P.ws + WS_TAB + (size_t)l * 32 * MB;
;   const unsigned char* V = U + 16 * MB;
;   bf16_t* hn = (bf16_t*)(P.ws + WS_HN);
;   const float* gp = P.norm_ple + l * DM;
;   const int row = lane >> 4, rmap = ((row & 1) << 1) | (row >> 1);
;   u32x4 nxa = *(const u32x4*)(hn + (size_t)(m0 + wid * 16) * DM + lane * 16), nxb = *(const u32x4*)(hn + (size_t)(m0 + wid * 16) * DM + lane * 16 + 8);
;   int ni0 = idxs[(wid * 16) * 128 + lane], ni1 = idxs[(wid * 16) * 128 + 64 + lane];
;   float ng0 = gs[(wid * 16) * 128 + lane], ng1 = gs[(wid * 16) * 128 + 64 + lane];
;   sort_lists(lane, ni0, ni1, ng0, ng1);
; #pragma nounroll
;   for (int i = 0; i < 16; ++i) {
;     const int tt = wid * 16 + i; const size_t tok = (size_t)(m0 + tt);
;     __syncthreads();
;     const u32x4 xa = nxa, xb = nxb;
;     f32x2_t xp[8];
; #pragma unroll
;     for (int q = 0; q < 4; ++q) { xp[q] = (f32x2_t){bflo(xa[q]), bfhi(xa[q])}; xp[4 + q] = (f32x2_t){bflo(xb[q]), bfhi(xb[q])}; }
;     const int myi0 = ni0, myi1 = ni1;
;     const float myg0 = ng0, myg1 = ng1;
;     f32x2_t acc[8];
; #pragma unroll
;     for (int q = 0; q < 8; ++q) acc[q] = (f32x2_t){0.f, 0.f};
;     float wr0 = 0.f, wr1 = 0.f;
;     u32x4 b0[8], b1[8];
;     ...
;     PG_ISSUE(b0, U, 0);
; #pragma nounroll
;     for (int e0 = 0; e0 < 128; e0 += 16) {
;       PG_ISSUE(b1, U, e0 + 8);
;       PG_U8(b0, 0, e0);
;       if (e0 + 16 < 128) PG_ISSUE(b0, U, e0 + 16); else PG_ISSUE(b0, V, 0);
;       PG_U8(b1, 0, e0 + 8);
;     }
.Lpg0_p0:
	s_lshl_b32 s98, s2, 11
	s_add_u32 s98, s98, s101
	v_add_u32_e32 v116, s98, v234
	ds_read_b32 v241, v116 offset:0
	ds_read_b32 v242, v116 offset:256
	ds_read_b32 v243, v116 offset:512
	ds_read_b32 v244, v116 offset:768
	ds_read_b32 v245, v116 offset:1024
	ds_read_b32 v246, v116 offset:1280
	ds_read_b32 v247, v116 offset:1536
	ds_read_b32 v248, v116 offset:1792
	s_waitcnt lgkmcnt(0)
	v_or_b32_e32 v116, 64, v233
	v_lshl_or_b32 v241, v241, 7, v233
	v_lshl_or_b32 v242, v242, 7, v116
	v_lshl_or_b32 v243, v243, 7, v233
	v_lshl_or_b32 v244, v244, 7, v116
	v_lshl_or_b32 v245, v245, 7, v233
	v_lshl_or_b32 v246, v246, 7, v116
	v_lshl_or_b32 v247, v247, 7, v233
	v_lshl_or_b32 v248, v248, 7, v116
	v_mov_b32_e32 v117, 0
	s_lshl_b32 s98, s2, 11
	s_add_u32 s98, s98, s101
	v_add_u32_e32 v116, s98, v234
	v_lshl_add_u32 v119, v235, 2, v237
	v_add_u32_e32 v119, s98, v119
	ds_write_b32 v119, v241 offset:0
	ds_write_b32 v119, v242 offset:32
	ds_write_b32 v119, v243 offset:512
	ds_write_b32 v119, v244 offset:544
	ds_write_b32 v119, v245 offset:1024
	ds_write_b32 v119, v246 offset:1056
	ds_write_b32 v119, v247 offset:1536
	ds_write_b32 v119, v248 offset:1568
	v_add_u32_e32 v118, 0x10000, v116
	ds_write_b32 v118, v117 offset:0
	ds_write_b32 v118, v117 offset:256
	ds_write_b32 v118, v117 offset:512
	ds_write_b32 v118, v117 offset:768
	ds_write_b32 v118, v117 offset:1024
	ds_write_b32 v118, v117 offset:1280
	ds_write_b32 v118, v117 offset:1536
	ds_write_b32 v118, v117 offset:1792
	s_add_u32 s2, s2, 1
	s_cmp_lt_u32 s2, 4
	s_cbranch_scc1 .Lpg0_p0
	s_waitcnt lgkmcnt(0)
	v_readfirstlane_b32 s82, v128
	v_readfirstlane_b32 s83, v129
	s_nop 4
	v_readfirstlane_b32 s80, v124
	v_readfirstlane_b32 s81, v125
	s_nop 4
	s_mov_b32 s2, 0xffffff80
	s_mov_b32 s86, 0xcccccccc
	s_mov_b32 s87, 0xcccccccc
	s_mov_b32 s88, 0xaaaaaaaa
	s_mov_b32 s89, 0xaaaaaaaa
	s_mov_b32 s90, 0xf0f0f0f0
	s_mov_b32 s91, 0xf0f0f0f0
	s_lshl_b32 vcc_lo, s3, 11
	s_add_u32 s82, s82, vcc_lo
	s_addc_u32 s83, s83, 0
	v_lshl_add_u32 v246, v237, 4, s101
	v_lshrrev_b32_e32 v247, 2, v235
	v_add_u32_e32 v247, v247, v246
	v_add_u32_e32 v247, 0x10000, v247
	s_mov_b32 s100, 0
	s_mov_b32 s98, 0
	s_mov_b32 s99, 0
	s_lshl3_add_u32 vcc_lo, s98, s99
	v_lshl_add_u32 v119, vcc_lo, 8, v236
	global_load_dwordx4 v[80:83], v119, s[82:83]
	global_load_dwordx4 v[84:87], v119, s[82:83] offset:16
	v_lshl_add_u32 v116, s98, 9, v246
	ds_read_b128 v[112:115], v116
	ds_read_b128 v[138:141], v116 offset:16
	ds_read_b128 v[250:253], v116 offset:32
	ds_read_b128 v[242:245], v116 offset:48
	v_lshl_or_b32 v240, s99, 21, v235
	s_waitcnt lgkmcnt(0)
	v_and_or_b32 v112, v112, s2, v240
	v_and_or_b32 v113, v113, s2, v240
	global_load_dwordx4 v[0:3], v112, s[80:81] sc1
	global_load_dwordx4 v[4:7], v113, s[80:81] sc1
	v_and_or_b32 v114, v114, s2, v240
	v_and_or_b32 v115, v115, s2, v240
	global_load_dwordx4 v[8:11], v114, s[80:81] sc1
	global_load_dwordx4 v[12:15], v115, s[80:81] sc1
	v_and_or_b32 v138, v138, s2, v240
	v_and_or_b32 v139, v139, s2, v240
	global_load_dwordx4 v[16:19], v138, s[80:81] sc1
	global_load_dwordx4 v[20:23], v139, s[80:81] sc1
	v_and_or_b32 v140, v140, s2, v240
	v_and_or_b32 v141, v141, s2, v240
	global_load_dwordx4 v[24:27], v140, s[80:81] sc1
	global_load_dwordx4 v[28:31], v141, s[80:81] sc1
	v_and_or_b32 v250, v250, s2, v240
	v_and_or_b32 v251, v251, s2, v240
	global_load_dwordx4 v[32:35], v250, s[80:81] sc1
	global_load_dwordx4 v[36:39], v251, s[80:81] sc1
	v_and_or_b32 v252, v252, s2, v240
	v_and_or_b32 v253, v253, s2, v240
	global_load_dwordx4 v[40:43], v252, s[80:81] sc1
	global_load_dwordx4 v[44:47], v253, s[80:81] sc1
	v_and_or_b32 v242, v242, s2, v240
	v_and_or_b32 v243, v243, s2, v240
	global_load_dwordx4 v[48:51], v242, s[80:81] sc1
	global_load_dwordx4 v[52:55], v243, s[80:81] sc1
	v_and_or_b32 v244, v244, s2, v240
	v_and_or_b32 v245, v245, s2, v240
	global_load_dwordx4 v[56:59], v244, s[80:81] sc1
	global_load_dwordx4 v[60:63], v245, s[80:81] sc1
	s_mov_b32 s92, 1
	v_lshl_add_u32 v116, s92, 9, v246
	ds_read_b128 v[112:115], v116
	ds_read_b128 v[138:141], v116 offset:16
	ds_read_b128 v[250:253], v116 offset:32
	ds_read_b128 v[242:245], v116 offset:48
.Lpg0_uloop:
	s_and_b32 s98, s100, 15
	s_add_u32 s92, s100, 1
	s_min_u32 s92, s92, 127
	s_lshr_b32 s93, s92, 4
	s_and_b32 s92, s92, 15
	s_waitcnt vmcnt(16) lgkmcnt(0)
	v_mov_b32_e32 v64, v80
	v_mov_b32_e32 v65, v81
	v_mov_b32_e32 v66, v82
	v_mov_b32_e32 v67, v83
	v_mov_b32_e32 v68, v84
	v_mov_b32_e32 v69, v85
	v_mov_b32_e32 v70, v86
	v_mov_b32_e32 v71, v87
	s_lshl3_add_u32 vcc_lo, s92, s93
	v_lshl_add_u32 v119, vcc_lo, 8, v236
	global_load_dwordx4 v[80:83], v119, s[82:83]
	global_load_dwordx4 v[84:87], v119, s[82:83] offset:16
	v_lshl_or_b32 v240, s93, 21, v235
	s_waitcnt vmcnt(16)
	v_cvt_scalef32_pk_bf16_fp8 v104, v0, 1.0
	v_cvt_scalef32_pk_bf16_fp8 v105, v0, 1.0 op_sel:[1,0,0]
	v_cvt_scalef32_pk_bf16_fp8 v106, v4, 1.0
	v_cvt_scalef32_pk_bf16_fp8 v107, v4, 1.0 op_sel:[1,0,0]
	v_cvt_scalef32_pk_bf16_fp8 v108, v1, 1.0
	v_cvt_scalef32_pk_bf16_fp8 v109, v1, 1.0 op_sel:[1,0,0]
	v_mfma_f32_4x4x4_16b_bf16 v[72:75], v[104:105], v[64:65], 0
	v_cvt_scalef32_pk_bf16_fp8 v110, v5, 1.0
	v_cvt_scalef32_pk_bf16_fp8 v111, v5, 1.0 op_sel:[1,0,0]
	v_mfma_f32_4x4x4_16b_bf16 v[76:79], v[106:107], v[64:65], 0
	v_cvt_scalef32_pk_bf16_fp8 v104, v2, 1.0
	v_cvt_scalef32_pk_bf16_fp8 v105, v2, 1.0 op_sel:[1,0,0]
	v_mfma_f32_4x4x4_16b_bf16 v[72:75], v[108:109], v[66:67], v[72:75]
	v_cvt_scalef32_pk_bf16_fp8 v106, v6, 1.0
	v_cvt_scalef32_pk_bf16_fp8 v107, v6, 1.0 op_sel:[1,0,0]
	v_mfma_f32_4x4x4_16b_bf16 v[76:79], v[110:111], v[66:67], v[76:79]
	v_cvt_scalef32_pk_bf16_fp8 v108, v3, 1.0
	v_cvt_scalef32_pk_bf16_fp8 v109, v3, 1.0 op_sel:[1,0,0]
	v_mfma_f32_4x4x4_16b_bf16 v[72:75], v[104:105], v[68:69], v[72:75]
	v_cvt_scalef32_pk_bf16_fp8 v110, v7, 1.0
	v_cvt_scalef32_pk_bf16_fp8 v111, v7, 1.0 op_sel:[1,0,0]
	v_mfma_f32_4x4x4_16b_bf16 v[76:79], v[106:107], v[68:69], v[76:79]
	v_and_or_b32 v112, v112, s2, v240
	v_and_or_b32 v113, v113, s2, v240
	global_load_dwordx4 v[0:3], v112, s[80:81] sc1
	global_load_dwordx4 v[4:7], v113, s[80:81] sc1
	s_waitcnt vmcnt(16)
	v_cvt_scalef32_pk_bf16_fp8 v104, v8, 1.0
	v_cvt_scalef32_pk_bf16_fp8 v105, v8, 1.0 op_sel:[1,0,0]
	v_mfma_f32_4x4x4_16b_bf16 v[72:75], v[108:109], v[70:71], v[72:75]
	v_cvt_scalef32_pk_bf16_fp8 v106, v12, 1.0
	v_cvt_scalef32_pk_bf16_fp8 v107, v12, 1.0 op_sel:[1,0,0]
	v_mfma_f32_4x4x4_16b_bf16 v[76:79], v[110:111], v[70:71], v[76:79]
	v_cvt_scalef32_pk_bf16_fp8 v108, v9, 1.0
	v_cvt_scalef32_pk_bf16_fp8 v109, v9, 1.0 op_sel:[1,0,0]
	v_cvt_scalef32_pk_bf16_fp8 v110, v13, 1.0
	v_cvt_scalef32_pk_bf16_fp8 v111, v13, 1.0 op_sel:[1,0,0]
	v_add_f32_dpp v148, v73, v72 quad_perm:[1,0,3,2] row_mask:0xf bank_mask:0xf
	v_add_f32_dpp v149, v75, v74 quad_perm:[1,0,3,2] row_mask:0xf bank_mask:0xf
	v_add_f32_dpp v150, v76, v77 quad_perm:[1,0,3,2] row_mask:0xf bank_mask:0xf
	v_add_f32_dpp v151, v78, v79 quad_perm:[1,0,3,2] row_mask:0xf bank_mask:0xf
	v_mfma_f32_4x4x4_16b_bf16 v[72:75], v[104:105], v[64:65], 0
	v_add_f32_dpp v88, v149, v148 quad_perm:[2,3,0,1] row_mask:0xf bank_mask:0xf
	v_mfma_f32_4x4x4_16b_bf16 v[76:79], v[106:107], v[64:65], 0
	v_add_f32_dpp v89, v151, v150 quad_perm:[2,3,0,1] row_mask:0xf bank_mask:0xf
	v_cvt_scalef32_pk_bf16_fp8 v104, v10, 1.0
	v_cvt_scalef32_pk_bf16_fp8 v105, v10, 1.0 op_sel:[1,0,0]
	v_mfma_f32_4x4x4_16b_bf16 v[72:75], v[108:109], v[66:67], v[72:75]
	v_cvt_scalef32_pk_bf16_fp8 v106, v14, 1.0
	v_cvt_scalef32_pk_bf16_fp8 v107, v14, 1.0 op_sel:[1,0,0]
	v_mfma_f32_4x4x4_16b_bf16 v[76:79], v[110:111], v[66:67], v[76:79]
	v_cvt_scalef32_pk_bf16_fp8 v108, v11, 1.0
	v_cvt_scalef32_pk_bf16_fp8 v109, v11, 1.0 op_sel:[1,0,0]
	v_mfma_f32_4x4x4_16b_bf16 v[72:75], v[104:105], v[68:69], v[72:75]
	v_cvt_scalef32_pk_bf16_fp8 v110, v15, 1.0
	v_cvt_scalef32_pk_bf16_fp8 v111, v15, 1.0 op_sel:[1,0,0]
	v_mfma_f32_4x4x4_16b_bf16 v[76:79], v[106:107], v[68:69], v[76:79]
	v_and_or_b32 v114, v114, s2, v240
	v_and_or_b32 v115, v115, s2, v240
	global_load_dwordx4 v[8:11], v114, s[80:81] sc1
	global_load_dwordx4 v[12:15], v115, s[80:81] sc1
	s_waitcnt vmcnt(16)
	v_cvt_scalef32_pk_bf16_fp8 v104, v16, 1.0
	v_cvt_scalef32_pk_bf16_fp8 v105, v16, 1.0 op_sel:[1,0,0]
	v_mfma_f32_4x4x4_16b_bf16 v[72:75], v[108:109], v[70:71], v[72:75]
	v_cvt_scalef32_pk_bf16_fp8 v106, v20, 1.0
	v_cvt_scalef32_pk_bf16_fp8 v107, v20, 1.0 op_sel:[1,0,0]
	v_mfma_f32_4x4x4_16b_bf16 v[76:79], v[110:111], v[70:71], v[76:79]
	v_cvt_scalef32_pk_bf16_fp8 v108, v17, 1.0
	v_cvt_scalef32_pk_bf16_fp8 v109, v17, 1.0 op_sel:[1,0,0]
	v_cvt_scalef32_pk_bf16_fp8 v110, v21, 1.0
	v_cvt_scalef32_pk_bf16_fp8 v111, v21, 1.0 op_sel:[1,0,0]
	v_add_f32_dpp v148, v75, v74 quad_perm:[1,0,3,2] row_mask:0xf bank_mask:0xf
	v_add_f32_dpp v149, v73, v72 quad_perm:[1,0,3,2] row_mask:0xf bank_mask:0xf
	v_add_f32_dpp v150, v78, v79 quad_perm:[1,0,3,2] row_mask:0xf bank_mask:0xf
	v_add_f32_dpp v151, v76, v77 quad_perm:[1,0,3,2] row_mask:0xf bank_mask:0xf
	v_mfma_f32_4x4x4_16b_bf16 v[72:75], v[104:105], v[64:65], 0
	v_add_f32_dpp v90, v149, v148 quad_perm:[2,3,0,1] row_mask:0xf bank_mask:0xf
	v_mfma_f32_4x4x4_16b_bf16 v[76:79], v[106:107], v[64:65], 0
	v_add_f32_dpp v91, v151, v150 quad_perm:[2,3,0,1] row_mask:0xf bank_mask:0xf
	v_cvt_scalef32_pk_bf16_fp8 v104, v18, 1.0
	v_cvt_scalef32_pk_bf16_fp8 v105, v18, 1.0 op_sel:[1,0,0]
	v_mfma_f32_4x4x4_16b_bf16 v[72:75], v[108:109], v[66:67], v[72:75]
	v_cvt_scalef32_pk_bf16_fp8 v106, v22, 1.0
	v_cvt_scalef32_pk_bf16_fp8 v107, v22, 1.0 op_sel:[1,0,0]
	v_mfma_f32_4x4x4_16b_bf16 v[76:79], v[110:111], v[66:67], v[76:79]
	v_cvt_scalef32_pk_bf16_fp8 v108, v19, 1.0
	v_cvt_scalef32_pk_bf16_fp8 v109, v19, 1.0 op_sel:[1,0,0]
	v_mfma_f32_4x4x4_16b_bf16 v[72:75], v[104:105], v[68:69], v[72:75]
	v_cvt_scalef32_pk_bf16_fp8 v110, v23, 1.0
	v_cvt_scalef32_pk_bf16_fp8 v111, v23, 1.0 op_sel:[1,0,0]
	v_mfma_f32_4x4x4_16b_bf16 v[76:79], v[106:107], v[68:69], v[76:79]
	v_and_or_b32 v138, v138, s2, v240
	v_and_or_b32 v139, v139, s2, v240
	global_load_dwordx4 v[16:19], v138, s[80:81] sc1
	global_load_dwordx4 v[20:23], v139, s[80:81] sc1
	s_waitcnt vmcnt(16)
	v_cvt_scalef32_pk_bf16_fp8 v104, v24, 1.0
	v_cvt_scalef32_pk_bf16_fp8 v105, v24, 1.0 op_sel:[1,0,0]
	v_mfma_f32_4x4x4_16b_bf16 v[72:75], v[108:109], v[70:71], v[72:75]
	v_cvt_scalef32_pk_bf16_fp8 v106, v28, 1.0
	v_cvt_scalef32_pk_bf16_fp8 v107, v28, 1.0 op_sel:[1,0,0]
	v_mfma_f32_4x4x4_16b_bf16 v[76:79], v[110:111], v[70:71], v[76:79]
	v_cvt_scalef32_pk_bf16_fp8 v108, v25, 1.0
	v_cvt_scalef32_pk_bf16_fp8 v109, v25, 1.0 op_sel:[1,0,0]
	v_cvt_scalef32_pk_bf16_fp8 v110, v29, 1.0
	v_cvt_scalef32_pk_bf16_fp8 v111, v29, 1.0 op_sel:[1,0,0]
	v_add_f32_dpp v148, v73, v72 quad_perm:[1,0,3,2] row_mask:0xf bank_mask:0xf
	v_add_f32_dpp v149, v75, v74 quad_perm:[1,0,3,2] row_mask:0xf bank_mask:0xf
	v_add_f32_dpp v150, v76, v77 quad_perm:[1,0,3,2] row_mask:0xf bank_mask:0xf
	v_add_f32_dpp v151, v78, v79 quad_perm:[1,0,3,2] row_mask:0xf bank_mask:0xf
	v_mfma_f32_4x4x4_16b_bf16 v[72:75], v[104:105], v[64:65], 0
	v_add_f32_dpp v92, v149, v148 quad_perm:[2,3,0,1] row_mask:0xf bank_mask:0xf
	v_mfma_f32_4x4x4_16b_bf16 v[76:79], v[106:107], v[64:65], 0
	v_add_f32_dpp v93, v151, v150 quad_perm:[2,3,0,1] row_mask:0xf bank_mask:0xf
	v_cvt_scalef32_pk_bf16_fp8 v104, v26, 1.0
	v_cvt_scalef32_pk_bf16_fp8 v105, v26, 1.0 op_sel:[1,0,0]
	v_mfma_f32_4x4x4_16b_bf16 v[72:75], v[108:109], v[66:67], v[72:75]
	v_cvt_scalef32_pk_bf16_fp8 v106, v30, 1.0
	v_cvt_scalef32_pk_bf16_fp8 v107, v30, 1.0 op_sel:[1,0,0]
	v_mfma_f32_4x4x4_16b_bf16 v[76:79], v[110:111], v[66:67], v[76:79]
	v_cvt_scalef32_pk_bf16_fp8 v108, v27, 1.0
	v_cvt_scalef32_pk_bf16_fp8 v109, v27, 1.0 op_sel:[1,0,0]
	v_mfma_f32_4x4x4_16b_bf16 v[72:75], v[104:105], v[68:69], v[72:75]
	v_cvt_scalef32_pk_bf16_fp8 v110, v31, 1.0
	v_cvt_scalef32_pk_bf16_fp8 v111, v31, 1.0 op_sel:[1,0,0]
	v_mfma_f32_4x4x4_16b_bf16 v[76:79], v[106:107], v[68:69], v[76:79]
	v_and_or_b32 v140, v140, s2, v240
	v_and_or_b32 v141, v141, s2, v240
	global_load_dwordx4 v[24:27], v140, s[80:81] sc1
	global_load_dwordx4 v[28:31], v141, s[80:81] sc1
	s_waitcnt vmcnt(16)
	v_cvt_scalef32_pk_bf16_fp8 v104, v32, 1.0
	v_cvt_scalef32_pk_bf16_fp8 v105, v32, 1.0 op_sel:[1,0,0]
	v_mfma_f32_4x4x4_16b_bf16 v[72:75], v[108:109], v[70:71], v[72:75]
	v_cvt_scalef32_pk_bf16_fp8 v106, v36, 1.0
	v_cvt_scalef32_pk_bf16_fp8 v107, v36, 1.0 op_sel:[1,0,0]
	v_mfma_f32_4x4x4_16b_bf16 v[76:79], v[110:111], v[70:71], v[76:79]
	v_cvt_scalef32_pk_bf16_fp8 v108, v33, 1.0
	v_cvt_scalef32_pk_bf16_fp8 v109, v33, 1.0 op_sel:[1,0,0]
	v_cvt_scalef32_pk_bf16_fp8 v110, v37, 1.0
	v_cvt_scalef32_pk_bf16_fp8 v111, v37, 1.0 op_sel:[1,0,0]
	v_add_f32_dpp v148, v75, v74 quad_perm:[1,0,3,2] row_mask:0xf bank_mask:0xf
	v_add_f32_dpp v149, v73, v72 quad_perm:[1,0,3,2] row_mask:0xf bank_mask:0xf
	v_add_f32_dpp v150, v78, v79 quad_perm:[1,0,3,2] row_mask:0xf bank_mask:0xf
	v_add_f32_dpp v151, v76, v77 quad_perm:[1,0,3,2] row_mask:0xf bank_mask:0xf
	v_mfma_f32_4x4x4_16b_bf16 v[72:75], v[104:105], v[64:65], 0
	v_add_f32_dpp v94, v149, v148 quad_perm:[2,3,0,1] row_mask:0xf bank_mask:0xf
	v_mfma_f32_4x4x4_16b_bf16 v[76:79], v[106:107], v[64:65], 0
	v_add_f32_dpp v95, v151, v150 quad_perm:[2,3,0,1] row_mask:0xf bank_mask:0xf
	v_cvt_scalef32_pk_bf16_fp8 v104, v34, 1.0
	v_cvt_scalef32_pk_bf16_fp8 v105, v34, 1.0 op_sel:[1,0,0]
	v_mfma_f32_4x4x4_16b_bf16 v[72:75], v[108:109], v[66:67], v[72:75]
	v_cvt_scalef32_pk_bf16_fp8 v106, v38, 1.0
	v_cvt_scalef32_pk_bf16_fp8 v107, v38, 1.0 op_sel:[1,0,0]
	v_mfma_f32_4x4x4_16b_bf16 v[76:79], v[110:111], v[66:67], v[76:79]
	v_cvt_scalef32_pk_bf16_fp8 v108, v35, 1.0
	v_cvt_scalef32_pk_bf16_fp8 v109, v35, 1.0 op_sel:[1,0,0]
	v_mfma_f32_4x4x4_16b_bf16 v[72:75], v[104:105], v[68:69], v[72:75]
	v_cvt_scalef32_pk_bf16_fp8 v110, v39, 1.0
	v_cvt_scalef32_pk_bf16_fp8 v111, v39, 1.0 op_sel:[1,0,0]
	v_mfma_f32_4x4x4_16b_bf16 v[76:79], v[106:107], v[68:69], v[76:79]
	v_and_or_b32 v250, v250, s2, v240
	v_and_or_b32 v251, v251, s2, v240
	global_load_dwordx4 v[32:35], v250, s[80:81] sc1
	global_load_dwordx4 v[36:39], v251, s[80:81] sc1
	s_waitcnt vmcnt(16)
	v_cvt_scalef32_pk_bf16_fp8 v104, v40, 1.0
	v_cvt_scalef32_pk_bf16_fp8 v105, v40, 1.0 op_sel:[1,0,0]
	v_mfma_f32_4x4x4_16b_bf16 v[72:75], v[108:109], v[70:71], v[72:75]
	v_cvt_scalef32_pk_bf16_fp8 v106, v44, 1.0
	v_cvt_scalef32_pk_bf16_fp8 v107, v44, 1.0 op_sel:[1,0,0]
	v_mfma_f32_4x4x4_16b_bf16 v[76:79], v[110:111], v[70:71], v[76:79]
	v_cvt_scalef32_pk_bf16_fp8 v108, v41, 1.0
	v_cvt_scalef32_pk_bf16_fp8 v109, v41, 1.0 op_sel:[1,0,0]
	v_cvt_scalef32_pk_bf16_fp8 v110, v45, 1.0
	v_cvt_scalef32_pk_bf16_fp8 v111, v45, 1.0 op_sel:[1,0,0]
	v_add_f32_dpp v148, v73, v72 quad_perm:[1,0,3,2] row_mask:0xf bank_mask:0xf
	v_add_f32_dpp v149, v75, v74 quad_perm:[1,0,3,2] row_mask:0xf bank_mask:0xf
	v_add_f32_dpp v150, v76, v77 quad_perm:[1,0,3,2] row_mask:0xf bank_mask:0xf
	v_add_f32_dpp v151, v78, v79 quad_perm:[1,0,3,2] row_mask:0xf bank_mask:0xf
	v_mfma_f32_4x4x4_16b_bf16 v[72:75], v[104:105], v[64:65], 0
	v_add_f32_dpp v96, v149, v148 quad_perm:[2,3,0,1] row_mask:0xf bank_mask:0xf
	v_mfma_f32_4x4x4_16b_bf16 v[76:79], v[106:107], v[64:65], 0
	v_add_f32_dpp v97, v151, v150 quad_perm:[2,3,0,1] row_mask:0xf bank_mask:0xf
	v_cvt_scalef32_pk_bf16_fp8 v104, v42, 1.0
	v_cvt_scalef32_pk_bf16_fp8 v105, v42, 1.0 op_sel:[1,0,0]
	v_mfma_f32_4x4x4_16b_bf16 v[72:75], v[108:109], v[66:67], v[72:75]
	v_cvt_scalef32_pk_bf16_fp8 v106, v46, 1.0
	v_cvt_scalef32_pk_bf16_fp8 v107, v46, 1.0 op_sel:[1,0,0]
	v_mfma_f32_4x4x4_16b_bf16 v[76:79], v[110:111], v[66:67], v[76:79]
	v_cvt_scalef32_pk_bf16_fp8 v108, v43, 1.0
	v_cvt_scalef32_pk_bf16_fp8 v109, v43, 1.0 op_sel:[1,0,0]
	v_mfma_f32_4x4x4_16b_bf16 v[72:75], v[104:105], v[68:69], v[72:75]
	v_cvt_scalef32_pk_bf16_fp8 v110, v47, 1.0
	v_cvt_scalef32_pk_bf16_fp8 v111, v47, 1.0 op_sel:[1,0,0]
	v_mfma_f32_4x4x4_16b_bf16 v[76:79], v[106:107], v[68:69], v[76:79]
	v_and_or_b32 v252, v252, s2, v240
	v_and_or_b32 v253, v253, s2, v240
	global_load_dwordx4 v[40:43], v252, s[80:81] sc1
	global_load_dwordx4 v[44:47], v253, s[80:81] sc1
	s_waitcnt vmcnt(16)
	v_cvt_scalef32_pk_bf16_fp8 v104, v48, 1.0
	v_cvt_scalef32_pk_bf16_fp8 v105, v48, 1.0 op_sel:[1,0,0]
	v_mfma_f32_4x4x4_16b_bf16 v[72:75], v[108:109], v[70:71], v[72:75]
	v_cvt_scalef32_pk_bf16_fp8 v106, v52, 1.0
	v_cvt_scalef32_pk_bf16_fp8 v107, v52, 1.0 op_sel:[1,0,0]
	v_mfma_f32_4x4x4_16b_bf16 v[76:79], v[110:111], v[70:71], v[76:79]
	v_cvt_scalef32_pk_bf16_fp8 v108, v49, 1.0
	v_cvt_scalef32_pk_bf16_fp8 v109, v49, 1.0 op_sel:[1,0,0]
	v_cvt_scalef32_pk_bf16_fp8 v110, v53, 1.0
	v_cvt_scalef32_pk_bf16_fp8 v111, v53, 1.0 op_sel:[1,0,0]
	v_add_f32_dpp v148, v75, v74 quad_perm:[1,0,3,2] row_mask:0xf bank_mask:0xf
	v_add_f32_dpp v149, v73, v72 quad_perm:[1,0,3,2] row_mask:0xf bank_mask:0xf
	v_add_f32_dpp v150, v78, v79 quad_perm:[1,0,3,2] row_mask:0xf bank_mask:0xf
	v_add_f32_dpp v151, v76, v77 quad_perm:[1,0,3,2] row_mask:0xf bank_mask:0xf
	v_mfma_f32_4x4x4_16b_bf16 v[72:75], v[104:105], v[64:65], 0
	v_add_f32_dpp v98, v149, v148 quad_perm:[2,3,0,1] row_mask:0xf bank_mask:0xf
	v_mfma_f32_4x4x4_16b_bf16 v[76:79], v[106:107], v[64:65], 0
	v_add_f32_dpp v99, v151, v150 quad_perm:[2,3,0,1] row_mask:0xf bank_mask:0xf
	v_cvt_scalef32_pk_bf16_fp8 v104, v50, 1.0
	v_cvt_scalef32_pk_bf16_fp8 v105, v50, 1.0 op_sel:[1,0,0]
	v_mfma_f32_4x4x4_16b_bf16 v[72:75], v[108:109], v[66:67], v[72:75]
	v_cvt_scalef32_pk_bf16_fp8 v106, v54, 1.0
	v_cvt_scalef32_pk_bf16_fp8 v107, v54, 1.0 op_sel:[1,0,0]
	v_mfma_f32_4x4x4_16b_bf16 v[76:79], v[110:111], v[66:67], v[76:79]
	v_cvt_scalef32_pk_bf16_fp8 v108, v51, 1.0
	v_cvt_scalef32_pk_bf16_fp8 v109, v51, 1.0 op_sel:[1,0,0]
	v_mfma_f32_4x4x4_16b_bf16 v[72:75], v[104:105], v[68:69], v[72:75]
	v_cvt_scalef32_pk_bf16_fp8 v110, v55, 1.0
	v_cvt_scalef32_pk_bf16_fp8 v111, v55, 1.0 op_sel:[1,0,0]
	v_mfma_f32_4x4x4_16b_bf16 v[76:79], v[106:107], v[68:69], v[76:79]
	v_and_or_b32 v242, v242, s2, v240
	v_and_or_b32 v243, v243, s2, v240
	global_load_dwordx4 v[48:51], v242, s[80:81] sc1
	global_load_dwordx4 v[52:55], v243, s[80:81] sc1
	s_waitcnt vmcnt(16)
; #define PG_ISSUE(BUF, TAB, e0_) do { const int isrc_ = ((e0_) < 64) ? myi0 : myi1; \
;       _Pragma("unroll") for (int e = 0; e < 8; ++e) { const int idx_ = __builtin_amdgcn_readlane(isrc_, ((e0_) + e) & 63); \
;         BUF[e] = *(const u32x4*)((TAB) + (size_t)idx_ * 1024 + lane * 16); } } while (0)
; DEV void peer_gather(const Params& P, int l, int m0, const int* idxs, const float* gs) {
;     ...
;     PG_ISSUE(b0, U, 0);
; #pragma nounroll
;     for (int e0 = 0; e0 < 128; e0 += 16) {
;       PG_ISSUE(b1, U, e0 + 8);
;       PG_U8(b0, 0, e0);
;       if (e0 + 16 < 128) PG_ISSUE(b0, U, e0 + 16); else PG_ISSUE(b0, V, 0);
;       PG_U8(b1, 0, e0 + 8);
;     }
	v_cvt_scalef32_pk_bf16_fp8 v104, v56, 1.0
	v_cvt_scalef32_pk_bf16_fp8 v105, v56, 1.0 op_sel:[1,0,0]
	v_mfma_f32_4x4x4_16b_bf16 v[72:75], v[108:109], v[70:71], v[72:75]
	v_cvt_scalef32_pk_bf16_fp8 v106, v60, 1.0
	v_cvt_scalef32_pk_bf16_fp8 v107, v60, 1.0 op_sel:[1,0,0]
	v_mfma_f32_4x4x4_16b_bf16 v[76:79], v[110:111], v[70:71], v[76:79]
	v_cvt_scalef32_pk_bf16_fp8 v108, v57, 1.0
	v_cvt_scalef32_pk_bf16_fp8 v109, v57, 1.0 op_sel:[1,0,0]
	v_cvt_scalef32_pk_bf16_fp8 v110, v61, 1.0
	v_cvt_scalef32_pk_bf16_fp8 v111, v61, 1.0 op_sel:[1,0,0]
	v_add_f32_dpp v148, v73, v72 quad_perm:[1,0,3,2] row_mask:0xf bank_mask:0xf
	v_add_f32_dpp v149, v75, v74 quad_perm:[1,0,3,2] row_mask:0xf bank_mask:0xf
	v_add_f32_dpp v150, v76, v77 quad_perm:[1,0,3,2] row_mask:0xf bank_mask:0xf
	v_add_f32_dpp v151, v78, v79 quad_perm:[1,0,3,2] row_mask:0xf bank_mask:0xf
	v_mfma_f32_4x4x4_16b_bf16 v[72:75], v[104:105], v[64:65], 0
	v_add_f32_dpp v100, v149, v148 quad_perm:[2,3,0,1] row_mask:0xf bank_mask:0xf
	v_mfma_f32_4x4x4_16b_bf16 v[76:79], v[106:107], v[64:65], 0
	v_add_f32_dpp v101, v151, v150 quad_perm:[2,3,0,1] row_mask:0xf bank_mask:0xf
	v_cvt_scalef32_pk_bf16_fp8 v104, v58, 1.0
	v_cvt_scalef32_pk_bf16_fp8 v105, v58, 1.0 op_sel:[1,0,0]
	v_mfma_f32_4x4x4_16b_bf16 v[72:75], v[108:109], v[66:67], v[72:75]
	v_cvt_scalef32_pk_bf16_fp8 v106, v62, 1.0
	v_cvt_scalef32_pk_bf16_fp8 v107, v62, 1.0 op_sel:[1,0,0]
	v_mfma_f32_4x4x4_16b_bf16 v[76:79], v[110:111], v[66:67], v[76:79]
	v_cvt_scalef32_pk_bf16_fp8 v108, v59, 1.0
	v_cvt_scalef32_pk_bf16_fp8 v109, v59, 1.0 op_sel:[1,0,0]
	v_mfma_f32_4x4x4_16b_bf16 v[72:75], v[104:105], v[68:69], v[72:75]
	v_cvt_scalef32_pk_bf16_fp8 v110, v63, 1.0
	v_cvt_scalef32_pk_bf16_fp8 v111, v63, 1.0 op_sel:[1,0,0]
	v_mfma_f32_4x4x4_16b_bf16 v[76:79], v[106:107], v[68:69], v[76:79]
	v_and_or_b32 v244, v244, s2, v240
	v_and_or_b32 v245, v245, s2, v240
	global_load_dwordx4 v[56:59], v244, s[80:81] sc1
	global_load_dwordx4 v[60:63], v245, s[80:81] sc1
	v_mfma_f32_4x4x4_16b_bf16 v[72:75], v[108:109], v[70:71], v[72:75]
	v_mfma_f32_4x4x4_16b_bf16 v[76:79], v[110:111], v[70:71], v[76:79]
	s_add_u32 s92, s100, 2
	s_and_b32 s92, s92, 15
	v_lshl_add_u32 v116, s92, 9, v246
	ds_read_b128 v[112:115], v116
	ds_read_b128 v[138:141], v116 offset:16
	ds_read_b128 v[250:253], v116 offset:32
	ds_read_b128 v[242:245], v116 offset:48
	v_lshl_add_u32 v117, s98, 9, v247
	ds_read_b32 v136, v117
	ds_read_b32 v137, v117 offset:32
	v_add_f32_dpp v148, v75, v74 quad_perm:[1,0,3,2] row_mask:0xf bank_mask:0xf
	v_add_f32_dpp v149, v73, v72 quad_perm:[1,0,3,2] row_mask:0xf bank_mask:0xf
	v_add_f32_dpp v150, v78, v79 quad_perm:[1,0,3,2] row_mask:0xf bank_mask:0xf
	v_add_f32_dpp v151, v76, v77 quad_perm:[1,0,3,2] row_mask:0xf bank_mask:0xf
	v_add_f32_dpp v102, v149, v148 quad_perm:[2,3,0,1] row_mask:0xf bank_mask:0xf
	s_nop 0
	v_add_f32_dpp v103, v151, v150 quad_perm:[2,3,0,1] row_mask:0xf bank_mask:0xf
	v_cndmask_b32_e64 v144, v88, v89, s[88:89]
	v_cndmask_b32_e64 v145, v90, v91, s[88:89]
	v_cndmask_b32_e64 v88, v144, v145, s[86:87]
	v_cndmask_b32_e64 v144, v92, v93, s[88:89]
	v_cndmask_b32_e64 v145, v94, v95, s[88:89]
	v_cndmask_b32_e64 v92, v144, v145, s[86:87]
	v_cndmask_b32_e64 v144, v96, v97, s[88:89]
	v_cndmask_b32_e64 v145, v98, v99, s[88:89]
	v_cndmask_b32_e64 v96, v144, v145, s[86:87]
	v_cndmask_b32_e64 v144, v100, v101, s[88:89]
	v_cndmask_b32_e64 v145, v102, v103, s[88:89]
	v_cndmask_b32_e64 v100, v144, v145, s[86:87]
	v_cndmask_b32_e64 v144, v88, v92, s[90:91]
	v_cndmask_b32_e64 v145, v92, v88, s[90:91]
	v_cndmask_b32_e64 v146, v96, v100, s[90:91]
	v_cndmask_b32_e64 v147, v100, v96, s[90:91]
	s_nop 1
	v_add_f32_dpp v88, v145, v144 row_shl:4 row_mask:0xf bank_mask:0x5
	v_add_f32_dpp v88, v145, v144 row_shr:4 row_mask:0xf bank_mask:0xa
	v_add_f32_dpp v96, v147, v146 row_shl:4 row_mask:0xf bank_mask:0x5
	v_add_f32_dpp v96, v147, v146 row_shr:4 row_mask:0xf bank_mask:0xa
	s_waitcnt lgkmcnt(0)
	v_add_f32_e32 v136, v136, v88
	v_add_f32_e32 v137, v137, v96
	ds_write_b32 v117, v136
	ds_write_b32 v117, v137 offset:32
	s_add_u32 s100, s100, 1
	s_cmp_lt_u32 s100, 128
	s_cbranch_scc1 .Lpg0_uloop
	s_waitcnt vmcnt(0) lgkmcnt(0)
	s_mov_b32 s2, 0
.Lpg0_act:
	v_readlane_b32 s82, v231, 28
	v_readlane_b32 s83, v231, 29
	s_nop 4
	s_lshl_b32 s98, s2, 11
	s_add_u32 s98, s98, s101
	v_add_u32_e32 v116, s98, v234
	v_add_u32_e32 v117, 0x10000, v116
	ds_read_b32 v0, v116 offset:0
	ds_read_b32 v8, v117 offset:0
	ds_read_b32 v1, v116 offset:256
	ds_read_b32 v9, v117 offset:256
	ds_read_b32 v2, v116 offset:512
	ds_read_b32 v10, v117 offset:512
	ds_read_b32 v3, v116 offset:768
	ds_read_b32 v11, v117 offset:768
	ds_read_b32 v4, v116 offset:1024
	ds_read_b32 v12, v117 offset:1024
	ds_read_b32 v5, v116 offset:1280
	ds_read_b32 v13, v117 offset:1280
	ds_read_b32 v6, v116 offset:1536
	ds_read_b32 v14, v117 offset:1536
	ds_read_b32 v7, v116 offset:1792
	ds_read_b32 v15, v117 offset:1792
	s_waitcnt lgkmcnt(0)
; #define PG_ISSUE(BUF, TAB, e0_) do { const int isrc_ = ((e0_) < 64) ? myi0 : myi1; \
;       _Pragma("unroll") for (int e = 0; e < 8; ++e) { const int idx_ = __builtin_amdgcn_readlane(isrc_, ((e0_) + e) & 63); \
;         BUF[e] = *(const u32x4*)((TAB) + (size_t)idx_ * 1024 + lane * 16); } } while (0)
; DEV void peer_gather(const Params& P, int l, int m0, const int* idxs, const float* gs) {
;     ...
;     PG_ISSUE(b0, U, 0);
; #pragma nounroll
;     for (int e0 = 0; e0 < 128; e0 += 16) {
;       PG_ISSUE(b1, U, e0 + 8);
;       PG_U8(b0, 0, e0);
;       if (e0 + 16 < 128) PG_ISSUE(b0, U, e0 + 16); else PG_ISSUE(b0, V, 0);
	s_lshl_b32 s99, s2, 2
	s_add_u32 s99, s99, s33
	s_add_u32 s99, s99, 0
	s_lshl_b32 s99, s99, 9
	v_and_b32_e32 v0, 0x7f, v0
	v_lshl_add_u32 v0, v0, 2, s99
	global_load_dword v16, v0, s[82:83]
	v_and_b32_e32 v1, 0x7f, v1
	v_lshl_add_u32 v1, v1, 2, s99
	global_load_dword v17, v1, s[82:83]
	s_lshl_b32 s99, s2, 2
	s_add_u32 s99, s99, s33
	s_add_u32 s99, s99, 1
	s_lshl_b32 s99, s99, 9
	v_and_b32_e32 v2, 0x7f, v2
	v_lshl_add_u32 v2, v2, 2, s99
	global_load_dword v18, v2, s[82:83]
	v_and_b32_e32 v3, 0x7f, v3
	v_lshl_add_u32 v3, v3, 2, s99
	global_load_dword v19, v3, s[82:83]
	s_lshl_b32 s99, s2, 2
	s_add_u32 s99, s99, s33
	s_add_u32 s99, s99, 2
	s_lshl_b32 s99, s99, 9
	v_and_b32_e32 v4, 0x7f, v4
	v_lshl_add_u32 v4, v4, 2, s99
	global_load_dword v20, v4, s[82:83]
	v_and_b32_e32 v5, 0x7f, v5
	v_lshl_add_u32 v5, v5, 2, s99
	global_load_dword v21, v5, s[82:83]
	s_lshl_b32 s99, s2, 2
	s_add_u32 s99, s99, s33
	s_add_u32 s99, s99, 3
	s_lshl_b32 s99, s99, 9
	v_and_b32_e32 v6, 0x7f, v6
	v_lshl_add_u32 v6, v6, 2, s99
	global_load_dword v22, v6, s[82:83]
	v_and_b32_e32 v7, 0x7f, v7
	v_lshl_add_u32 v7, v7, 2, s99
	global_load_dword v23, v7, s[82:83]
	v_mul_f32_e32 v8, 0x3c800000, v8
	v_mul_f32_e32 v9, 0x3c800000, v9
	v_mul_f32_e32 v10, 0x3c800000, v10
	v_mul_f32_e32 v11, 0x3c800000, v11
	v_mul_f32_e32 v12, 0x3c800000, v12
	v_mul_f32_e32 v13, 0x3c800000, v13
	v_mul_f32_e32 v14, 0x3c800000, v14
	v_mul_f32_e32 v15, 0x3c800000, v15
	v_mul_f32_e32 v24, 0x3d372713, v8
	v_mul_f32_e32 v25, 0x3d372713, v9
	v_mul_f32_e32 v26, 0x3d372713, v10
	v_mul_f32_e32 v27, 0x3d372713, v11
	v_mul_f32_e32 v28, 0x3d372713, v12
	v_mul_f32_e32 v29, 0x3d372713, v13
	v_mul_f32_e32 v30, 0x3d372713, v14
	v_mul_f32_e32 v31, 0x3d372713, v15
	v_mul_f32_e32 v24, v8, v24
	v_mul_f32_e32 v25, v9, v25
	v_mul_f32_e32 v26, v10, v26
	v_mul_f32_e32 v27, v11, v27
	v_mul_f32_e32 v28, v12, v28
	v_mul_f32_e32 v29, v13, v29
	v_mul_f32_e32 v30, v14, v30
	v_mul_f32_e32 v31, v15, v31
	v_fma_f32 v24, v8, v24, v8
	v_fma_f32 v25, v9, v25, v9
	v_fma_f32 v26, v10, v26, v10
	v_fma_f32 v27, v11, v27, v11
	v_fma_f32 v28, v12, v28, v12
	v_fma_f32 v29, v13, v29, v13
	v_fma_f32 v30, v14, v30, v14
	v_fma_f32 v31, v15, v31, v15
	v_mul_f32_e32 v24, 0xbfcc422a, v24
	v_mul_f32_e32 v25, 0xbfcc422a, v25
	v_mul_f32_e32 v26, 0xbfcc422a, v26
	v_mul_f32_e32 v27, 0xbfcc422a, v27
	v_mul_f32_e32 v28, 0xbfcc422a, v28
	v_mul_f32_e32 v29, 0xbfcc422a, v29
	v_mul_f32_e32 v30, 0xbfcc422a, v30
	v_mul_f32_e32 v31, 0xbfcc422a, v31
	v_mul_f32_e32 v24, 0x3fb8aa3b, v24
	v_mul_f32_e32 v25, 0x3fb8aa3b, v25
	v_mul_f32_e32 v26, 0x3fb8aa3b, v26
	v_mul_f32_e32 v27, 0x3fb8aa3b, v27
	v_mul_f32_e32 v28, 0x3fb8aa3b, v28
	v_mul_f32_e32 v29, 0x3fb8aa3b, v29
	v_mul_f32_e32 v30, 0x3fb8aa3b, v30
	v_mul_f32_e32 v31, 0x3fb8aa3b, v31
	v_exp_f32_e32 v24, v24
	v_exp_f32_e32 v25, v25
	v_exp_f32_e32 v26, v26
	v_exp_f32_e32 v27, v27
	v_exp_f32_e32 v28, v28
	v_exp_f32_e32 v29, v29
	v_exp_f32_e32 v30, v30
	v_exp_f32_e32 v31, v31
	s_nop 0
	v_add_f32_e32 v24, 1.0, v24
	v_add_f32_e32 v25, 1.0, v25
	v_add_f32_e32 v26, 1.0, v26
	v_add_f32_e32 v27, 1.0, v27
	v_add_f32_e32 v28, 1.0, v28
	v_add_f32_e32 v29, 1.0, v29
	v_add_f32_e32 v30, 1.0, v30
	v_add_f32_e32 v31, 1.0, v31
	v_rcp_f32_e32 v24, v24
	v_rcp_f32_e32 v25, v25
	v_rcp_f32_e32 v26, v26
	v_rcp_f32_e32 v27, v27
	v_rcp_f32_e32 v28, v28
	v_rcp_f32_e32 v29, v29
	v_rcp_f32_e32 v30, v30
	v_rcp_f32_e32 v31, v31
	s_nop 0
	v_mul_f32_e32 v24, v8, v24
	v_mul_f32_e32 v25, v9, v25
	v_mul_f32_e32 v26, v10, v26
	v_mul_f32_e32 v27, v11, v27
	v_mul_f32_e32 v28, v12, v28
	v_mul_f32_e32 v29, v13, v29
	v_mul_f32_e32 v30, v14, v30
	v_mul_f32_e32 v31, v15, v31
	s_waitcnt vmcnt(0)
	v_mul_f32_e32 v24, v24, v16
	ds_write_b32 v117, v24 offset:0
	v_mul_f32_e32 v25, v25, v17
	ds_write_b32 v117, v25 offset:256
	v_mul_f32_e32 v26, v26, v18
	ds_write_b32 v117, v26 offset:512
	v_mul_f32_e32 v27, v27, v19
	ds_write_b32 v117, v27 offset:768
	v_mul_f32_e32 v28, v28, v20
	ds_write_b32 v117, v28 offset:1024
	v_mul_f32_e32 v29, v29, v21
	ds_write_b32 v117, v29 offset:1280
	v_mul_f32_e32 v30, v30, v22
	ds_write_b32 v117, v30 offset:1536
	v_mul_f32_e32 v31, v31, v23
	ds_write_b32 v117, v31 offset:1792
	s_add_u32 s2, s2, 1
	s_cmp_lt_u32 s2, 4
	s_cbranch_scc1 .Lpg0_act
	s_waitcnt lgkmcnt(0)
	v_readfirstlane_b32 s80, v126
	v_readfirstlane_b32 s81, v127
	s_nop 4
	v_readfirstlane_b32 s82, v132
	v_readfirstlane_b32 s83, v133
	s_nop 4
	s_mov_b32 s2, 0xffffff80
	s_lshl_b32 vcc_lo, s3, 12
	s_add_u32 s82, s82, vcc_lo
	s_addc_u32 s83, s83, 0
	s_mov_b32 s88, 0xff00ff00
	s_mov_b32 s89, 0xff00ff00
	v_lshl_add_u32 v246, v237, 4, s101
	v_add_u32_e32 v247, 0x10000, v246
	v_lshlrev_b32_e32 v238, 2, v235
	v_bfe_u32 v116, v233, 5, 1
	v_lshl_add_u32 v238, v116, 3, v238
	v_bfe_u32 v116, v233, 4, 1
	v_lshl_add_u32 v238, v116, 4, v238
	v_bfe_u32 v116, v233, 3, 1
	v_lshl_add_u32 v238, v116, 5, v238
	s_mov_b32 s100, 0
	s_mov_b32 s98, 0
	s_mov_b32 s99, 0
	v_lshl_add_u32 v116, s98, 9, v246
	ds_read_b128 v[112:115], v116
	ds_read_b128 v[138:141], v116 offset:16
	ds_read_b128 v[250:253], v116 offset:32
	ds_read_b128 v[242:245], v116 offset:48
	v_lshl_or_b32 v240, s99, 21, v235
	s_waitcnt lgkmcnt(0)
	v_and_or_b32 v112, v112, s2, v240
	v_and_or_b32 v113, v113, s2, v240
	global_load_dwordx4 v[0:3], v112, s[80:81] sc1
	global_load_dwordx4 v[4:7], v113, s[80:81] sc1
	v_and_or_b32 v114, v114, s2, v240
	v_and_or_b32 v115, v115, s2, v240
	global_load_dwordx4 v[8:11], v114, s[80:81] sc1
	global_load_dwordx4 v[12:15], v115, s[80:81] sc1
	v_and_or_b32 v138, v138, s2, v240
	v_and_or_b32 v139, v139, s2, v240
	global_load_dwordx4 v[16:19], v138, s[80:81] sc1
	global_load_dwordx4 v[20:23], v139, s[80:81] sc1
	v_and_or_b32 v140, v140, s2, v240
	v_and_or_b32 v141, v141, s2, v240
	global_load_dwordx4 v[24:27], v140, s[80:81] sc1
	global_load_dwordx4 v[28:31], v141, s[80:81] sc1
	v_and_or_b32 v250, v250, s2, v240
	v_and_or_b32 v251, v251, s2, v240
	global_load_dwordx4 v[32:35], v250, s[80:81] sc1
	global_load_dwordx4 v[36:39], v251, s[80:81] sc1
	v_and_or_b32 v252, v252, s2, v240
	v_and_or_b32 v253, v253, s2, v240
	global_load_dwordx4 v[40:43], v252, s[80:81] sc1
	global_load_dwordx4 v[44:47], v253, s[80:81] sc1
	v_and_or_b32 v242, v242, s2, v240
	v_and_or_b32 v243, v243, s2, v240
	global_load_dwordx4 v[48:51], v242, s[80:81] sc1
	global_load_dwordx4 v[52:55], v243, s[80:81] sc1
	v_and_or_b32 v244, v244, s2, v240
	v_and_or_b32 v245, v245, s2, v240
	global_load_dwordx4 v[56:59], v244, s[80:81] sc1
	global_load_dwordx4 v[60:63], v245, s[80:81] sc1
	s_mov_b32 s92, 1
	v_lshl_add_u32 v116, s92, 9, v246
	ds_read_b128 v[112:115], v116
	ds_read_b128 v[138:141], v116 offset:16
	ds_read_b128 v[250:253], v116 offset:32
	ds_read_b128 v[242:245], v116 offset:48
	v_lshl_add_u32 v117, s98, 9, v247
	ds_read_b128 v[84:87], v117
	ds_read_b128 v[88:91], v117 offset:16
	ds_read_b128 v[92:95], v117 offset:32
	ds_read_b128 v[96:99], v117 offset:48
	s_waitcnt vmcnt(0)
; #define PG_ISSUE(BUF, TAB, e0_) do { const int isrc_ = ((e0_) < 64) ? myi0 : myi1; \
;       _Pragma("unroll") for (int e = 0; e < 8; ++e) { const int idx_ = __builtin_amdgcn_readlane(isrc_, ((e0_) + e) & 63); \
;         BUF[e] = *(const u32x4*)((TAB) + (size_t)idx_ * 1024 + lane * 16); } } while (0)
; DEV void peer_gather(const Params& P, int l, int m0, const int* idxs, const float* gs) {
;     ...
;     PG_ISSUE(b0, U, 0);
; #pragma nounroll
;     for (int e0 = 0; e0 < 128; e0 += 16) {
;       PG_ISSUE(b1, U, e0 + 8);
;       PG_U8(b0, 0, e0);
;       if (e0 + 16 < 128) PG_ISSUE(b0, U, e0 + 16); else PG_ISSUE(b0, V, 0);
;       PG_U8(b1, 0, e0 + 8);
;     }
;     float* hrow = P.out + tok * DM + lane * 16;
;     f32x4 hv[4];
; #pragma unroll
;     for (int q = 0; q < 4; ++q) hv[q] = *(const f32x4*)(hrow + 4 * q);
;     if (i + 1 < 16) {
;       const int tn = tt + 1;
;       nxa = *(const u32x4*)(hn + (size_t)(m0 + tn) * DM + lane * 16); nxb = *(const u32x4*)(hn + (size_t)(m0 + tn) * DM + lane * 16 + 8);
;       ni0 = idxs[tn * 128 + lane]; ni1 = idxs[tn * 128 + 64 + lane]; ng0 = gs[tn * 128 + lane]; ng1 = gs[tn * 128 + 64 + lane];
;     }
; #pragma nounroll
;     for (int e0 = 0; e0 < 128; e0 += 16) {
;       PG_ISSUE(b1, V, e0 + 8);
;       if (e0 == 64 && i + 1 < 16) sort_lists(lane, ni0, ni1, ng0, ng1);
;       PG_V16(b0, e0);
;       if (e0 + 16 < 128) PG_ISSUE(b0, V, e0 + 16);
;       PG_V16(b1, e0 + 8);
;     }
.Lpg0_vloop:
	s_and_b32 s98, s100, 15
	s_lshr_b32 s99, s100, 4
	s_add_u32 s93, s100, 1
	s_min_u32 s93, s93, 127
	s_lshr_b32 s93, s93, 4
	s_lshl3_add_u32 vcc_lo, s98, s99
	v_lshl_add_u32 v119, vcc_lo, 9, v238
	global_load_dwordx2 v[80:81], v119, s[82:83]
	v_lshl_or_b32 v240, s93, 21, v235
	s_waitcnt lgkmcnt(0)
	s_waitcnt vmcnt(16)
	v_cvt_pk_f32_fp8_e32 v[104:105], v0
	v_cvt_pk_f32_fp8_e32 v[108:109], v4
	v_cvt_pk_f32_fp8_sdwa v[106:107], v0 src0_sel:WORD_1
	v_cvt_pk_f32_fp8_sdwa v[110:111], v4 src0_sel:WORD_1
	v_pk_mul_f32 v[64:65], v[104:105], v[84:85] op_sel_hi:[1,0]
	v_pk_mul_f32 v[66:67], v[106:107], v[84:85] op_sel_hi:[1,0]
	v_pk_fma_f32 v[64:65], v[108:109], v[84:85], v[64:65] op_sel:[0,1,0] op_sel_hi:[1,1,1]
	v_pk_fma_f32 v[66:67], v[110:111], v[84:85], v[66:67] op_sel:[0,1,0] op_sel_hi:[1,1,1]
	v_cvt_pk_f32_fp8_e32 v[104:105], v1
	v_cvt_pk_f32_fp8_e32 v[108:109], v5
	v_cvt_pk_f32_fp8_sdwa v[106:107], v1 src0_sel:WORD_1
	v_cvt_pk_f32_fp8_sdwa v[110:111], v5 src0_sel:WORD_1
	v_pk_mul_f32 v[68:69], v[104:105], v[84:85] op_sel_hi:[1,0]
	v_pk_mul_f32 v[70:71], v[106:107], v[84:85] op_sel_hi:[1,0]
	v_pk_fma_f32 v[68:69], v[108:109], v[84:85], v[68:69] op_sel:[0,1,0] op_sel_hi:[1,1,1]
	v_pk_fma_f32 v[70:71], v[110:111], v[84:85], v[70:71] op_sel:[0,1,0] op_sel_hi:[1,1,1]
	v_cvt_pk_f32_fp8_e32 v[104:105], v2
	v_cvt_pk_f32_fp8_e32 v[108:109], v6
	v_cvt_pk_f32_fp8_sdwa v[106:107], v2 src0_sel:WORD_1
	v_cvt_pk_f32_fp8_sdwa v[110:111], v6 src0_sel:WORD_1
	v_pk_mul_f32 v[72:73], v[104:105], v[84:85] op_sel_hi:[1,0]
	v_pk_mul_f32 v[74:75], v[106:107], v[84:85] op_sel_hi:[1,0]
	v_pk_fma_f32 v[72:73], v[108:109], v[84:85], v[72:73] op_sel:[0,1,0] op_sel_hi:[1,1,1]
	v_pk_fma_f32 v[74:75], v[110:111], v[84:85], v[74:75] op_sel:[0,1,0] op_sel_hi:[1,1,1]
	v_cvt_pk_f32_fp8_e32 v[104:105], v3
	v_cvt_pk_f32_fp8_e32 v[108:109], v7
	v_cvt_pk_f32_fp8_sdwa v[106:107], v3 src0_sel:WORD_1
	v_cvt_pk_f32_fp8_sdwa v[110:111], v7 src0_sel:WORD_1
	v_pk_mul_f32 v[76:77], v[104:105], v[84:85] op_sel_hi:[1,0]
	v_pk_mul_f32 v[78:79], v[106:107], v[84:85] op_sel_hi:[1,0]
	v_and_or_b32 v112, v112, s2, v240
	v_and_or_b32 v113, v113, s2, v240
	global_load_dwordx4 v[0:3], v112, s[80:81] sc1
	global_load_dwordx4 v[4:7], v113, s[80:81] sc1
	v_pk_fma_f32 v[76:77], v[108:109], v[84:85], v[76:77] op_sel:[0,1,0] op_sel_hi:[1,1,1]
	v_pk_fma_f32 v[78:79], v[110:111], v[84:85], v[78:79] op_sel:[0,1,0] op_sel_hi:[1,1,1]
	s_waitcnt vmcnt(16)
	v_cvt_pk_f32_fp8_e32 v[104:105], v8
	v_cvt_pk_f32_fp8_e32 v[108:109], v12
	v_cvt_pk_f32_fp8_sdwa v[106:107], v8 src0_sel:WORD_1
	v_cvt_pk_f32_fp8_sdwa v[110:111], v12 src0_sel:WORD_1
	v_pk_fma_f32 v[64:65], v[104:105], v[86:87], v[64:65] op_sel_hi:[1,0,1]
	v_pk_fma_f32 v[66:67], v[106:107], v[86:87], v[66:67] op_sel_hi:[1,0,1]
	v_pk_fma_f32 v[64:65], v[108:109], v[86:87], v[64:65] op_sel:[0,1,0] op_sel_hi:[1,1,1]
	v_pk_fma_f32 v[66:67], v[110:111], v[86:87], v[66:67] op_sel:[0,1,0] op_sel_hi:[1,1,1]
	v_cvt_pk_f32_fp8_e32 v[104:105], v9
	v_cvt_pk_f32_fp8_e32 v[108:109], v13
	v_cvt_pk_f32_fp8_sdwa v[106:107], v9 src0_sel:WORD_1
	v_cvt_pk_f32_fp8_sdwa v[110:111], v13 src0_sel:WORD_1
	v_pk_fma_f32 v[68:69], v[104:105], v[86:87], v[68:69] op_sel_hi:[1,0,1]
	v_pk_fma_f32 v[70:71], v[106:107], v[86:87], v[70:71] op_sel_hi:[1,0,1]
	v_pk_fma_f32 v[68:69], v[108:109], v[86:87], v[68:69] op_sel:[0,1,0] op_sel_hi:[1,1,1]
	v_pk_fma_f32 v[70:71], v[110:111], v[86:87], v[70:71] op_sel:[0,1,0] op_sel_hi:[1,1,1]
	v_cvt_pk_f32_fp8_e32 v[104:105], v10
	v_cvt_pk_f32_fp8_e32 v[108:109], v14
	v_cvt_pk_f32_fp8_sdwa v[106:107], v10 src0_sel:WORD_1
	v_cvt_pk_f32_fp8_sdwa v[110:111], v14 src0_sel:WORD_1
	v_pk_fma_f32 v[72:73], v[104:105], v[86:87], v[72:73] op_sel_hi:[1,0,1]
	v_pk_fma_f32 v[74:75], v[106:107], v[86:87], v[74:75] op_sel_hi:[1,0,1]
	v_pk_fma_f32 v[72:73], v[108:109], v[86:87], v[72:73] op_sel:[0,1,0] op_sel_hi:[1,1,1]
	v_pk_fma_f32 v[74:75], v[110:111], v[86:87], v[74:75] op_sel:[0,1,0] op_sel_hi:[1,1,1]
	v_cvt_pk_f32_fp8_e32 v[104:105], v11
	v_cvt_pk_f32_fp8_e32 v[108:109], v15
	v_cvt_pk_f32_fp8_sdwa v[106:107], v11 src0_sel:WORD_1
	v_cvt_pk_f32_fp8_sdwa v[110:111], v15 src0_sel:WORD_1
	v_pk_fma_f32 v[76:77], v[104:105], v[86:87], v[76:77] op_sel_hi:[1,0,1]
	v_pk_fma_f32 v[78:79], v[106:107], v[86:87], v[78:79] op_sel_hi:[1,0,1]
	v_and_or_b32 v114, v114, s2, v240
	v_and_or_b32 v115, v115, s2, v240
	global_load_dwordx4 v[8:11], v114, s[80:81] sc1
	global_load_dwordx4 v[12:15], v115, s[80:81] sc1
	v_pk_fma_f32 v[76:77], v[108:109], v[86:87], v[76:77] op_sel:[0,1,0] op_sel_hi:[1,1,1]
	v_pk_fma_f32 v[78:79], v[110:111], v[86:87], v[78:79] op_sel:[0,1,0] op_sel_hi:[1,1,1]
	s_waitcnt vmcnt(16)
	v_cvt_pk_f32_fp8_e32 v[104:105], v16
	v_cvt_pk_f32_fp8_e32 v[108:109], v20
	v_cvt_pk_f32_fp8_sdwa v[106:107], v16 src0_sel:WORD_1
	v_cvt_pk_f32_fp8_sdwa v[110:111], v20 src0_sel:WORD_1
	v_pk_fma_f32 v[64:65], v[104:105], v[88:89], v[64:65] op_sel_hi:[1,0,1]
	v_pk_fma_f32 v[66:67], v[106:107], v[88:89], v[66:67] op_sel_hi:[1,0,1]
	v_pk_fma_f32 v[64:65], v[108:109], v[88:89], v[64:65] op_sel:[0,1,0] op_sel_hi:[1,1,1]
	v_pk_fma_f32 v[66:67], v[110:111], v[88:89], v[66:67] op_sel:[0,1,0] op_sel_hi:[1,1,1]
	v_cvt_pk_f32_fp8_e32 v[104:105], v17
	v_cvt_pk_f32_fp8_e32 v[108:109], v21
	v_cvt_pk_f32_fp8_sdwa v[106:107], v17 src0_sel:WORD_1
	v_cvt_pk_f32_fp8_sdwa v[110:111], v21 src0_sel:WORD_1
	v_pk_fma_f32 v[68:69], v[104:105], v[88:89], v[68:69] op_sel_hi:[1,0,1]
	v_pk_fma_f32 v[70:71], v[106:107], v[88:89], v[70:71] op_sel_hi:[1,0,1]
	v_pk_fma_f32 v[68:69], v[108:109], v[88:89], v[68:69] op_sel:[0,1,0] op_sel_hi:[1,1,1]
	v_pk_fma_f32 v[70:71], v[110:111], v[88:89], v[70:71] op_sel:[0,1,0] op_sel_hi:[1,1,1]
	v_cvt_pk_f32_fp8_e32 v[104:105], v18
	v_cvt_pk_f32_fp8_e32 v[108:109], v22
	v_cvt_pk_f32_fp8_sdwa v[106:107], v18 src0_sel:WORD_1
	v_cvt_pk_f32_fp8_sdwa v[110:111], v22 src0_sel:WORD_1
	v_pk_fma_f32 v[72:73], v[104:105], v[88:89], v[72:73] op_sel_hi:[1,0,1]
	v_pk_fma_f32 v[74:75], v[106:107], v[88:89], v[74:75] op_sel_hi:[1,0,1]
	v_pk_fma_f32 v[72:73], v[108:109], v[88:89], v[72:73] op_sel:[0,1,0] op_sel_hi:[1,1,1]
	v_pk_fma_f32 v[74:75], v[110:111], v[88:89], v[74:75] op_sel:[0,1,0] op_sel_hi:[1,1,1]
	v_cvt_pk_f32_fp8_e32 v[104:105], v19
	v_cvt_pk_f32_fp8_e32 v[108:109], v23
	v_cvt_pk_f32_fp8_sdwa v[106:107], v19 src0_sel:WORD_1
	v_cvt_pk_f32_fp8_sdwa v[110:111], v23 src0_sel:WORD_1
	v_pk_fma_f32 v[76:77], v[104:105], v[88:89], v[76:77] op_sel_hi:[1,0,1]
	v_pk_fma_f32 v[78:79], v[106:107], v[88:89], v[78:79] op_sel_hi:[1,0,1]
	v_and_or_b32 v138, v138, s2, v240
	v_and_or_b32 v139, v139, s2, v240
	global_load_dwordx4 v[16:19], v138, s[80:81] sc1
	global_load_dwordx4 v[20:23], v139, s[80:81] sc1
	v_pk_fma_f32 v[76:77], v[108:109], v[88:89], v[76:77] op_sel:[0,1,0] op_sel_hi:[1,1,1]
	v_pk_fma_f32 v[78:79], v[110:111], v[88:89], v[78:79] op_sel:[0,1,0] op_sel_hi:[1,1,1]
	s_waitcnt vmcnt(16)
	v_cvt_pk_f32_fp8_e32 v[104:105], v24
	v_cvt_pk_f32_fp8_e32 v[108:109], v28
	v_cvt_pk_f32_fp8_sdwa v[106:107], v24 src0_sel:WORD_1
	v_cvt_pk_f32_fp8_sdwa v[110:111], v28 src0_sel:WORD_1
	v_pk_fma_f32 v[64:65], v[104:105], v[90:91], v[64:65] op_sel_hi:[1,0,1]
	v_pk_fma_f32 v[66:67], v[106:107], v[90:91], v[66:67] op_sel_hi:[1,0,1]
	v_pk_fma_f32 v[64:65], v[108:109], v[90:91], v[64:65] op_sel:[0,1,0] op_sel_hi:[1,1,1]
	v_pk_fma_f32 v[66:67], v[110:111], v[90:91], v[66:67] op_sel:[0,1,0] op_sel_hi:[1,1,1]
	v_cvt_pk_f32_fp8_e32 v[104:105], v25
	v_cvt_pk_f32_fp8_e32 v[108:109], v29
	v_cvt_pk_f32_fp8_sdwa v[106:107], v25 src0_sel:WORD_1
	v_cvt_pk_f32_fp8_sdwa v[110:111], v29 src0_sel:WORD_1
	v_pk_fma_f32 v[68:69], v[104:105], v[90:91], v[68:69] op_sel_hi:[1,0,1]
	v_pk_fma_f32 v[70:71], v[106:107], v[90:91], v[70:71] op_sel_hi:[1,0,1]
	v_pk_fma_f32 v[68:69], v[108:109], v[90:91], v[68:69] op_sel:[0,1,0] op_sel_hi:[1,1,1]
	v_pk_fma_f32 v[70:71], v[110:111], v[90:91], v[70:71] op_sel:[0,1,0] op_sel_hi:[1,1,1]
	v_cvt_pk_f32_fp8_e32 v[104:105], v26
	v_cvt_pk_f32_fp8_e32 v[108:109], v30
	v_cvt_pk_f32_fp8_sdwa v[106:107], v26 src0_sel:WORD_1
	v_cvt_pk_f32_fp8_sdwa v[110:111], v30 src0_sel:WORD_1
	v_pk_fma_f32 v[72:73], v[104:105], v[90:91], v[72:73] op_sel_hi:[1,0,1]
	v_pk_fma_f32 v[74:75], v[106:107], v[90:91], v[74:75] op_sel_hi:[1,0,1]
	v_pk_fma_f32 v[72:73], v[108:109], v[90:91], v[72:73] op_sel:[0,1,0] op_sel_hi:[1,1,1]
	v_pk_fma_f32 v[74:75], v[110:111], v[90:91], v[74:75] op_sel:[0,1,0] op_sel_hi:[1,1,1]
	v_cvt_pk_f32_fp8_e32 v[104:105], v27
	v_cvt_pk_f32_fp8_e32 v[108:109], v31
	v_cvt_pk_f32_fp8_sdwa v[106:107], v27 src0_sel:WORD_1
	v_cvt_pk_f32_fp8_sdwa v[110:111], v31 src0_sel:WORD_1
	v_pk_fma_f32 v[76:77], v[104:105], v[90:91], v[76:77] op_sel_hi:[1,0,1]
	v_pk_fma_f32 v[78:79], v[106:107], v[90:91], v[78:79] op_sel_hi:[1,0,1]
	v_and_or_b32 v140, v140, s2, v240
	v_and_or_b32 v141, v141, s2, v240
	global_load_dwordx4 v[24:27], v140, s[80:81] sc1
	global_load_dwordx4 v[28:31], v141, s[80:81] sc1
	v_pk_fma_f32 v[76:77], v[108:109], v[90:91], v[76:77] op_sel:[0,1,0] op_sel_hi:[1,1,1]
	v_pk_fma_f32 v[78:79], v[110:111], v[90:91], v[78:79] op_sel:[0,1,0] op_sel_hi:[1,1,1]
	s_waitcnt vmcnt(16)
	v_cvt_pk_f32_fp8_e32 v[104:105], v32
	v_cvt_pk_f32_fp8_e32 v[108:109], v36
	v_cvt_pk_f32_fp8_sdwa v[106:107], v32 src0_sel:WORD_1
	v_cvt_pk_f32_fp8_sdwa v[110:111], v36 src0_sel:WORD_1
	v_pk_fma_f32 v[64:65], v[104:105], v[92:93], v[64:65] op_sel_hi:[1,0,1]
	v_pk_fma_f32 v[66:67], v[106:107], v[92:93], v[66:67] op_sel_hi:[1,0,1]
	v_pk_fma_f32 v[64:65], v[108:109], v[92:93], v[64:65] op_sel:[0,1,0] op_sel_hi:[1,1,1]
	v_pk_fma_f32 v[66:67], v[110:111], v[92:93], v[66:67] op_sel:[0,1,0] op_sel_hi:[1,1,1]
	v_cvt_pk_f32_fp8_e32 v[104:105], v33
	v_cvt_pk_f32_fp8_e32 v[108:109], v37
	v_cvt_pk_f32_fp8_sdwa v[106:107], v33 src0_sel:WORD_1
	v_cvt_pk_f32_fp8_sdwa v[110:111], v37 src0_sel:WORD_1
	v_pk_fma_f32 v[68:69], v[104:105], v[92:93], v[68:69] op_sel_hi:[1,0,1]
	v_pk_fma_f32 v[70:71], v[106:107], v[92:93], v[70:71] op_sel_hi:[1,0,1]
	v_pk_fma_f32 v[68:69], v[108:109], v[92:93], v[68:69] op_sel:[0,1,0] op_sel_hi:[1,1,1]
	v_pk_fma_f32 v[70:71], v[110:111], v[92:93], v[70:71] op_sel:[0,1,0] op_sel_hi:[1,1,1]
	v_cvt_pk_f32_fp8_e32 v[104:105], v34
	v_cvt_pk_f32_fp8_e32 v[108:109], v38
	v_cvt_pk_f32_fp8_sdwa v[106:107], v34 src0_sel:WORD_1
	v_cvt_pk_f32_fp8_sdwa v[110:111], v38 src0_sel:WORD_1
	v_pk_fma_f32 v[72:73], v[104:105], v[92:93], v[72:73] op_sel_hi:[1,0,1]
	v_pk_fma_f32 v[74:75], v[106:107], v[92:93], v[74:75] op_sel_hi:[1,0,1]
	v_pk_fma_f32 v[72:73], v[108:109], v[92:93], v[72:73] op_sel:[0,1,0] op_sel_hi:[1,1,1]
	v_pk_fma_f32 v[74:75], v[110:111], v[92:93], v[74:75] op_sel:[0,1,0] op_sel_hi:[1,1,1]
	v_cvt_pk_f32_fp8_e32 v[104:105], v35
	v_cvt_pk_f32_fp8_e32 v[108:109], v39
	v_cvt_pk_f32_fp8_sdwa v[106:107], v35 src0_sel:WORD_1
	v_cvt_pk_f32_fp8_sdwa v[110:111], v39 src0_sel:WORD_1
	v_pk_fma_f32 v[76:77], v[104:105], v[92:93], v[76:77] op_sel_hi:[1,0,1]
	v_pk_fma_f32 v[78:79], v[106:107], v[92:93], v[78:79] op_sel_hi:[1,0,1]
	v_and_or_b32 v250, v250, s2, v240
	v_and_or_b32 v251, v251, s2, v240
	global_load_dwordx4 v[32:35], v250, s[80:81] sc1
	global_load_dwordx4 v[36:39], v251, s[80:81] sc1
	v_pk_fma_f32 v[76:77], v[108:109], v[92:93], v[76:77] op_sel:[0,1,0] op_sel_hi:[1,1,1]
	v_pk_fma_f32 v[78:79], v[110:111], v[92:93], v[78:79] op_sel:[0,1,0] op_sel_hi:[1,1,1]
	s_waitcnt vmcnt(16)
	v_cvt_pk_f32_fp8_e32 v[104:105], v40
	v_cvt_pk_f32_fp8_e32 v[108:109], v44
	v_cvt_pk_f32_fp8_sdwa v[106:107], v40 src0_sel:WORD_1
	v_cvt_pk_f32_fp8_sdwa v[110:111], v44 src0_sel:WORD_1
	v_pk_fma_f32 v[64:65], v[104:105], v[94:95], v[64:65] op_sel_hi:[1,0,1]
	v_pk_fma_f32 v[66:67], v[106:107], v[94:95], v[66:67] op_sel_hi:[1,0,1]
	v_pk_fma_f32 v[64:65], v[108:109], v[94:95], v[64:65] op_sel:[0,1,0] op_sel_hi:[1,1,1]
	v_pk_fma_f32 v[66:67], v[110:111], v[94:95], v[66:67] op_sel:[0,1,0] op_sel_hi:[1,1,1]
	v_cvt_pk_f32_fp8_e32 v[104:105], v41
	v_cvt_pk_f32_fp8_e32 v[108:109], v45
	v_cvt_pk_f32_fp8_sdwa v[106:107], v41 src0_sel:WORD_1
	v_cvt_pk_f32_fp8_sdwa v[110:111], v45 src0_sel:WORD_1
	v_pk_fma_f32 v[68:69], v[104:105], v[94:95], v[68:69] op_sel_hi:[1,0,1]
	v_pk_fma_f32 v[70:71], v[106:107], v[94:95], v[70:71] op_sel_hi:[1,0,1]
	v_pk_fma_f32 v[68:69], v[108:109], v[94:95], v[68:69] op_sel:[0,1,0] op_sel_hi:[1,1,1]
	v_pk_fma_f32 v[70:71], v[110:111], v[94:95], v[70:71] op_sel:[0,1,0] op_sel_hi:[1,1,1]
	v_cvt_pk_f32_fp8_e32 v[104:105], v42
	v_cvt_pk_f32_fp8_e32 v[108:109], v46
	v_cvt_pk_f32_fp8_sdwa v[106:107], v42 src0_sel:WORD_1
	v_cvt_pk_f32_fp8_sdwa v[110:111], v46 src0_sel:WORD_1
	v_pk_fma_f32 v[72:73], v[104:105], v[94:95], v[72:73] op_sel_hi:[1,0,1]
	v_pk_fma_f32 v[74:75], v[106:107], v[94:95], v[74:75] op_sel_hi:[1,0,1]
	v_pk_fma_f32 v[72:73], v[108:109], v[94:95], v[72:73] op_sel:[0,1,0] op_sel_hi:[1,1,1]
	v_pk_fma_f32 v[74:75], v[110:111], v[94:95], v[74:75] op_sel:[0,1,0] op_sel_hi:[1,1,1]
	v_cvt_pk_f32_fp8_e32 v[104:105], v43
	v_cvt_pk_f32_fp8_e32 v[108:109], v47
	v_cvt_pk_f32_fp8_sdwa v[106:107], v43 src0_sel:WORD_1
	v_cvt_pk_f32_fp8_sdwa v[110:111], v47 src0_sel:WORD_1
	v_pk_fma_f32 v[76:77], v[104:105], v[94:95], v[76:77] op_sel_hi:[1,0,1]
	v_pk_fma_f32 v[78:79], v[106:107], v[94:95], v[78:79] op_sel_hi:[1,0,1]
	v_and_or_b32 v252, v252, s2, v240
	v_and_or_b32 v253, v253, s2, v240
	global_load_dwordx4 v[40:43], v252, s[80:81] sc1
	global_load_dwordx4 v[44:47], v253, s[80:81] sc1
	v_pk_fma_f32 v[76:77], v[108:109], v[94:95], v[76:77] op_sel:[0,1,0] op_sel_hi:[1,1,1]
	v_pk_fma_f32 v[78:79], v[110:111], v[94:95], v[78:79] op_sel:[0,1,0] op_sel_hi:[1,1,1]
	s_waitcnt vmcnt(16)
	v_cvt_pk_f32_fp8_e32 v[104:105], v48
	v_cvt_pk_f32_fp8_e32 v[108:109], v52
	v_cvt_pk_f32_fp8_sdwa v[106:107], v48 src0_sel:WORD_1
	v_cvt_pk_f32_fp8_sdwa v[110:111], v52 src0_sel:WORD_1
	v_pk_fma_f32 v[64:65], v[104:105], v[96:97], v[64:65] op_sel_hi:[1,0,1]
	v_pk_fma_f32 v[66:67], v[106:107], v[96:97], v[66:67] op_sel_hi:[1,0,1]
	v_pk_fma_f32 v[64:65], v[108:109], v[96:97], v[64:65] op_sel:[0,1,0] op_sel_hi:[1,1,1]
	v_pk_fma_f32 v[66:67], v[110:111], v[96:97], v[66:67] op_sel:[0,1,0] op_sel_hi:[1,1,1]
	v_cvt_pk_f32_fp8_e32 v[104:105], v49
	v_cvt_pk_f32_fp8_e32 v[108:109], v53
	v_cvt_pk_f32_fp8_sdwa v[106:107], v49 src0_sel:WORD_1
	v_cvt_pk_f32_fp8_sdwa v[110:111], v53 src0_sel:WORD_1
	v_pk_fma_f32 v[68:69], v[104:105], v[96:97], v[68:69] op_sel_hi:[1,0,1]
	v_pk_fma_f32 v[70:71], v[106:107], v[96:97], v[70:71] op_sel_hi:[1,0,1]
	v_pk_fma_f32 v[68:69], v[108:109], v[96:97], v[68:69] op_sel:[0,1,0] op_sel_hi:[1,1,1]
	v_pk_fma_f32 v[70:71], v[110:111], v[96:97], v[70:71] op_sel:[0,1,0] op_sel_hi:[1,1,1]
	v_cvt_pk_f32_fp8_e32 v[104:105], v50
	v_cvt_pk_f32_fp8_e32 v[108:109], v54
	v_cvt_pk_f32_fp8_sdwa v[106:107], v50 src0_sel:WORD_1
	v_cvt_pk_f32_fp8_sdwa v[110:111], v54 src0_sel:WORD_1
	v_pk_fma_f32 v[72:73], v[104:105], v[96:97], v[72:73] op_sel_hi:[1,0,1]
	v_pk_fma_f32 v[74:75], v[106:107], v[96:97], v[74:75] op_sel_hi:[1,0,1]
	v_pk_fma_f32 v[72:73], v[108:109], v[96:97], v[72:73] op_sel:[0,1,0] op_sel_hi:[1,1,1]
	v_pk_fma_f32 v[74:75], v[110:111], v[96:97], v[74:75] op_sel:[0,1,0] op_sel_hi:[1,1,1]
	v_cvt_pk_f32_fp8_e32 v[104:105], v51
	v_cvt_pk_f32_fp8_e32 v[108:109], v55
	v_cvt_pk_f32_fp8_sdwa v[106:107], v51 src0_sel:WORD_1
	v_cvt_pk_f32_fp8_sdwa v[110:111], v55 src0_sel:WORD_1
	v_pk_fma_f32 v[76:77], v[104:105], v[96:97], v[76:77] op_sel_hi:[1,0,1]
	v_pk_fma_f32 v[78:79], v[106:107], v[96:97], v[78:79] op_sel_hi:[1,0,1]
	v_and_or_b32 v242, v242, s2, v240
	v_and_or_b32 v243, v243, s2, v240
	global_load_dwordx4 v[48:51], v242, s[80:81] sc1
	global_load_dwordx4 v[52:55], v243, s[80:81] sc1
	v_pk_fma_f32 v[76:77], v[108:109], v[96:97], v[76:77] op_sel:[0,1,0] op_sel_hi:[1,1,1]
	v_pk_fma_f32 v[78:79], v[110:111], v[96:97], v[78:79] op_sel:[0,1,0] op_sel_hi:[1,1,1]
	s_waitcnt vmcnt(16)
; DEV unsigned pk2(float lo, float hi) { f32x2_t v = {lo, hi}; bf16x2_t b = __builtin_convertvector(v, bf16x2_t); return __builtin_bit_cast(unsigned, b); }
; DEV void peer_gather(const Params& P, int l, int m0, const int* idxs, const float* gs) {
;     ...
;     PG_ISSUE(b0, U, 0);
; #pragma nounroll
;     for (int e0 = 0; e0 < 128; e0 += 16) {
;       PG_ISSUE(b1, U, e0 + 8);
;       PG_U8(b0, 0, e0);
;       if (e0 + 16 < 128) PG_ISSUE(b0, U, e0 + 16); else PG_ISSUE(b0, V, 0);
;       PG_U8(b1, 0, e0 + 8);
;     }
;     float* hrow = P.out + tok * DM + lane * 16;
;     f32x4 hv[4];
; #pragma unroll
;     for (int q = 0; q < 4; ++q) hv[q] = *(const f32x4*)(hrow + 4 * q);
;     if (i + 1 < 16) {
;       const int tn = tt + 1;
;       nxa = *(const u32x4*)(hn + (size_t)(m0 + tn) * DM + lane * 16); nxb = *(const u32x4*)(hn + (size_t)(m0 + tn) * DM + lane * 16 + 8);
;       ni0 = idxs[tn * 128 + lane]; ni1 = idxs[tn * 128 + 64 + lane]; ng0 = gs[tn * 128 + lane]; ng1 = gs[tn * 128 + 64 + lane];
;     }
; #pragma nounroll
;     for (int e0 = 0; e0 < 128; e0 += 16) {
;       PG_ISSUE(b1, V, e0 + 8);
;       if (e0 == 64 && i + 1 < 16) sort_lists(lane, ni0, ni1, ng0, ng1);
;       PG_V16(b0, e0);
;       if (e0 + 16 < 128) PG_ISSUE(b0, V, e0 + 16);
;       PG_V16(b1, e0 + 8);
;     }
;     ...
;     float ss = 0.f;
; #pragma unroll
;     for (int q = 0; q < 4; ++q) {
;       hv[q][0] += acc[2 * q][0] * TAB_INV; hv[q][1] += acc[2 * q][1] * TAB_INV; hv[q][2] += acc[2 * q + 1][0] * TAB_INV; hv[q][3] += acc[2 * q + 1][1] * TAB_INV;
;       ss += hv[q][0] * hv[q][0] + hv[q][1] * hv[q][1] + hv[q][2] * hv[q][2] + hv[q][3] * hv[q][3];
;       *(f32x4*)(hrow + 4 * q) = hv[q];
;     }
;     const float rstd = rsqrtf(wave_sum(ss) * (1.f / DM) + EPS);
;     u32x4 oa, ob;
; #pragma unroll
;     for (int q = 0; q < 4; ++q) {
;       const f32x4 g = *(const f32x4*)(gp + lane * 16 + 4 * q);
;       const unsigned p0 = pk2(hv[q][0] * rstd * g[0], hv[q][1] * rstd * g[1]), p1 = pk2(hv[q][2] * rstd * g[2], hv[q][3] * rstd * g[3]);
;       if (q < 2) { oa[2 * q] = p0; oa[2 * q + 1] = p1; } else { ob[2 * (q - 2)] = p0; ob[2 * (q - 2) + 1] = p1; }
;     }
;     *(u32x4*)(hn + tok * DM + lane * 16) = oa; *(u32x4*)(hn + tok * DM + lane * 16 + 8) = ob;
	v_cvt_pk_f32_fp8_e32 v[104:105], v56
	v_cvt_pk_f32_fp8_e32 v[108:109], v60
	v_cvt_pk_f32_fp8_sdwa v[106:107], v56 src0_sel:WORD_1
	v_cvt_pk_f32_fp8_sdwa v[110:111], v60 src0_sel:WORD_1
	v_pk_fma_f32 v[64:65], v[104:105], v[98:99], v[64:65] op_sel_hi:[1,0,1]
	v_pk_fma_f32 v[66:67], v[106:107], v[98:99], v[66:67] op_sel_hi:[1,0,1]
	v_pk_fma_f32 v[64:65], v[108:109], v[98:99], v[64:65] op_sel:[0,1,0] op_sel_hi:[1,1,1]
	v_pk_fma_f32 v[66:67], v[110:111], v[98:99], v[66:67] op_sel:[0,1,0] op_sel_hi:[1,1,1]
	v_cvt_pk_f32_fp8_e32 v[104:105], v57
	v_cvt_pk_f32_fp8_e32 v[108:109], v61
	v_cvt_pk_f32_fp8_sdwa v[106:107], v57 src0_sel:WORD_1
	v_cvt_pk_f32_fp8_sdwa v[110:111], v61 src0_sel:WORD_1
	v_pk_fma_f32 v[68:69], v[104:105], v[98:99], v[68:69] op_sel_hi:[1,0,1]
	v_pk_fma_f32 v[70:71], v[106:107], v[98:99], v[70:71] op_sel_hi:[1,0,1]
	v_pk_fma_f32 v[68:69], v[108:109], v[98:99], v[68:69] op_sel:[0,1,0] op_sel_hi:[1,1,1]
	v_pk_fma_f32 v[70:71], v[110:111], v[98:99], v[70:71] op_sel:[0,1,0] op_sel_hi:[1,1,1]
	v_cvt_pk_f32_fp8_e32 v[104:105], v58
	v_cvt_pk_f32_fp8_e32 v[108:109], v62
	v_cvt_pk_f32_fp8_sdwa v[106:107], v58 src0_sel:WORD_1
	v_cvt_pk_f32_fp8_sdwa v[110:111], v62 src0_sel:WORD_1
	v_pk_fma_f32 v[72:73], v[104:105], v[98:99], v[72:73] op_sel_hi:[1,0,1]
	v_pk_fma_f32 v[74:75], v[106:107], v[98:99], v[74:75] op_sel_hi:[1,0,1]
	v_pk_fma_f32 v[72:73], v[108:109], v[98:99], v[72:73] op_sel:[0,1,0] op_sel_hi:[1,1,1]
	v_pk_fma_f32 v[74:75], v[110:111], v[98:99], v[74:75] op_sel:[0,1,0] op_sel_hi:[1,1,1]
	v_cvt_pk_f32_fp8_e32 v[104:105], v59
	v_cvt_pk_f32_fp8_e32 v[108:109], v63
	v_cvt_pk_f32_fp8_sdwa v[106:107], v59 src0_sel:WORD_1
	v_cvt_pk_f32_fp8_sdwa v[110:111], v63 src0_sel:WORD_1
	v_pk_fma_f32 v[76:77], v[104:105], v[98:99], v[76:77] op_sel_hi:[1,0,1]
	v_pk_fma_f32 v[78:79], v[106:107], v[98:99], v[78:79] op_sel_hi:[1,0,1]
	v_and_or_b32 v244, v244, s2, v240
	v_and_or_b32 v245, v245, s2, v240
	global_load_dwordx4 v[56:59], v244, s[80:81] sc1
	global_load_dwordx4 v[60:63], v245, s[80:81] sc1
	v_pk_fma_f32 v[76:77], v[108:109], v[98:99], v[76:77] op_sel:[0,1,0] op_sel_hi:[1,1,1]
	v_pk_fma_f32 v[78:79], v[110:111], v[98:99], v[78:79] op_sel:[0,1,0] op_sel_hi:[1,1,1]
	s_add_u32 s92, s100, 2
	s_and_b32 s92, s92, 15
	v_lshl_add_u32 v116, s92, 9, v246
	ds_read_b128 v[112:115], v116
	ds_read_b128 v[138:141], v116 offset:16
	ds_read_b128 v[250:253], v116 offset:32
	ds_read_b128 v[242:245], v116 offset:48
	s_add_u32 s92, s100, 1
	s_and_b32 s92, s92, 15
	v_lshl_add_u32 v117, s92, 9, v247
	ds_read_b128 v[84:87], v117
	ds_read_b128 v[88:91], v117 offset:16
	ds_read_b128 v[92:95], v117 offset:32
	ds_read_b128 v[96:99], v117 offset:48
	s_nop 1
	v_permlane32_swap_b32_e32 v64, v66
	v_permlane32_swap_b32_e32 v65, v67
	v_permlane32_swap_b32_e32 v68, v70
	v_permlane32_swap_b32_e32 v69, v71
	v_permlane32_swap_b32_e32 v72, v74
	v_permlane32_swap_b32_e32 v73, v75
	v_permlane32_swap_b32_e32 v76, v78
	v_permlane32_swap_b32_e32 v77, v79
	v_add_f32_e32 v64, v64, v66
	v_add_f32_e32 v65, v65, v67
	v_add_f32_e32 v68, v68, v70
	v_add_f32_e32 v69, v69, v71
	v_add_f32_e32 v72, v72, v74
	v_add_f32_e32 v73, v73, v75
	v_add_f32_e32 v76, v76, v78
	v_add_f32_e32 v77, v77, v79
	s_nop 1
	v_permlane16_swap_b32_e32 v64, v68
	v_permlane16_swap_b32_e32 v65, v69
	v_permlane16_swap_b32_e32 v72, v76
	v_permlane16_swap_b32_e32 v73, v77
	v_add_f32_e32 v64, v64, v68
	v_add_f32_e32 v65, v65, v69
	v_add_f32_e32 v72, v72, v76
	v_add_f32_e32 v73, v73, v77
	s_nop 0
	v_cndmask_b32_e64 v66, v64, v72, s[88:89]
	v_cndmask_b32_e64 v67, v72, v64, s[88:89]
	v_cndmask_b32_e64 v74, v65, v73, s[88:89]
	v_cndmask_b32_e64 v75, v73, v65, s[88:89]
	s_nop 1
	v_add_f32_dpp v64, v67, v66 row_ror:8 row_mask:0xf bank_mask:0xf
	v_add_f32_dpp v65, v75, v74 row_ror:8 row_mask:0xf bank_mask:0xf
	s_waitcnt vmcnt(16)
	v_fmac_f32_e32 v80, 0x3c800000, v64
	v_fmac_f32_e32 v81, 0x3c800000, v65
	global_store_dwordx2 v119, v[80:81], s[82:83]
	s_add_u32 s100, s100, 1
	s_cmp_lt_u32 s100, 128
	s_cbranch_scc1 .Lpg0_vloop
	s_waitcnt vmcnt(0) lgkmcnt(0)
	v_readfirstlane_b32 s88, v130
	v_readfirstlane_b32 s89, v131
	s_nop 4
	v_lshlrev_b32_e32 v117, 6, v233
	global_load_dwordx4 v[16:19], v117, s[88:89] offset:0
	global_load_dwordx4 v[20:23], v117, s[88:89] offset:16
	global_load_dwordx4 v[24:27], v117, s[88:89] offset:32
	global_load_dwordx4 v[28:31], v117, s[88:89] offset:48
	s_mov_b32 s2, 0

; DEV float bflo(unsigned u) { return __uint_as_float(u << 16); }
; DEV float bfhi(unsigned u) { return __uint_as_float(u & 0xffff0000u); }
; DEV int tid_l() { int t = threadIdx.x; asm volatile("" : "+v"(t)); return t; }
; #define PG_ISSUE(BUF, TAB, e0_) do { const int isrc_ = ((e0_) < 64) ? myi0 : myi1; \
;       _Pragma("unroll") for (int e = 0; e < 8; ++e) { const int idx_ = __builtin_amdgcn_readlane(isrc_, ((e0_) + e) & 63); \
;         BUF[e] = *(const u32x4*)((TAB) + (size_t)idx_ * 1024 + lane * 16); } } while (0)
; DEV void peer_gather(const Params& P, int l, int m0, const int* idxs, const float* gs) {
;   const int tid = tid_l(), lane = tid & 63, wid = tid >> 6;
;   const unsigned char* U = P.ws + WS_TAB + (size_t)l * 32 * MB;
;   const unsigned char* V = U + 16 * MB;
;   bf16_t* hn = (bf16_t*)(P.ws + WS_HN);
;   const float* gp = P.norm_ple + l * DM;
;   const int row = lane >> 4, rmap = ((row & 1) << 1) | (row >> 1);
;   u32x4 nxa = *(const u32x4*)(hn + (size_t)(m0 + wid * 16) * DM + lane * 16), nxb = *(const u32x4*)(hn + (size_t)(m0 + wid * 16) * DM + lane * 16 + 8);
;   int ni0 = idxs[(wid * 16) * 128 + lane], ni1 = idxs[(wid * 16) * 128 + 64 + lane];
;   float ng0 = gs[(wid * 16) * 128 + lane], ng1 = gs[(wid * 16) * 128 + 64 + lane];
;   sort_lists(lane, ni0, ni1, ng0, ng1);
; #pragma nounroll
;   for (int i = 0; i < 16; ++i) {
;     const int tt = wid * 16 + i; const size_t tok = (size_t)(m0 + tt);
;     __syncthreads();
;     const u32x4 xa = nxa, xb = nxb;
;     f32x2_t xp[8];
; #pragma unroll
;     for (int q = 0; q < 4; ++q) { xp[q] = (f32x2_t){bflo(xa[q]), bfhi(xa[q])}; xp[4 + q] = (f32x2_t){bflo(xb[q]), bfhi(xb[q])}; }
;     const int myi0 = ni0, myi1 = ni1;
;     const float myg0 = ng0, myg1 = ng1;
;     f32x2_t acc[8];
; #pragma unroll
;     for (int q = 0; q < 8; ++q) acc[q] = (f32x2_t){0.f, 0.f};
;     float wr0 = 0.f, wr1 = 0.f;
;     u32x4 b0[8], b1[8];
;     ...
;     PG_ISSUE(b0, U, 0);
; #pragma nounroll
;     for (int e0 = 0; e0 < 128; e0 += 16) {
;       PG_ISSUE(b1, U, e0 + 8);
;       PG_U8(b0, 0, e0);
;       if (e0 + 16 < 128) PG_ISSUE(b0, U, e0 + 16); else PG_ISSUE(b0, V, 0);
;       PG_U8(b1, 0, e0 + 8);
;     }
.Lpg1_p0:
	s_lshl_b32 s98, s2, 11
	s_add_u32 s98, s98, s101
	v_add_u32_e32 v116, s98, v234
	ds_read_b32 v241, v116 offset:0
	ds_read_b32 v242, v116 offset:256
	ds_read_b32 v243, v116 offset:512
	ds_read_b32 v244, v116 offset:768
	ds_read_b32 v245, v116 offset:1024
	ds_read_b32 v246, v116 offset:1280
	ds_read_b32 v247, v116 offset:1536
	ds_read_b32 v248, v116 offset:1792
	s_waitcnt lgkmcnt(0)
	v_or_b32_e32 v116, 64, v233
	v_lshl_or_b32 v241, v241, 7, v233
	v_lshl_or_b32 v242, v242, 7, v116
	v_lshl_or_b32 v243, v243, 7, v233
	v_lshl_or_b32 v244, v244, 7, v116
	v_lshl_or_b32 v245, v245, 7, v233
	v_lshl_or_b32 v246, v246, 7, v116
	v_lshl_or_b32 v247, v247, 7, v233
	v_lshl_or_b32 v248, v248, 7, v116
	v_mov_b32_e32 v117, 0
	s_lshl_b32 s98, s2, 11
	s_add_u32 s98, s98, s101
	v_add_u32_e32 v116, s98, v234
	v_lshl_add_u32 v119, v235, 2, v237
	v_add_u32_e32 v119, s98, v119
	ds_write_b32 v119, v241 offset:0
	ds_write_b32 v119, v242 offset:32
	ds_write_b32 v119, v243 offset:512
	ds_write_b32 v119, v244 offset:544
	ds_write_b32 v119, v245 offset:1024
	ds_write_b32 v119, v246 offset:1056
	ds_write_b32 v119, v247 offset:1536
	ds_write_b32 v119, v248 offset:1568
	v_add_u32_e32 v118, 0x10000, v116
	ds_write_b32 v118, v117 offset:0
	ds_write_b32 v118, v117 offset:256
	ds_write_b32 v118, v117 offset:512
	ds_write_b32 v118, v117 offset:768
	ds_write_b32 v118, v117 offset:1024
	ds_write_b32 v118, v117 offset:1280
	ds_write_b32 v118, v117 offset:1536
	ds_write_b32 v118, v117 offset:1792
	s_add_u32 s2, s2, 1
	s_cmp_lt_u32 s2, 4
	s_cbranch_scc1 .Lpg1_p0
	s_waitcnt lgkmcnt(0)
	v_readfirstlane_b32 s82, v122
	v_readfirstlane_b32 s83, v123
	s_nop 4
	v_readfirstlane_b32 s80, v126
	v_readfirstlane_b32 s81, v127
	s_nop 4
	s_mov_b32 s2, 0xffffff80
	s_mov_b32 s86, 0xcccccccc
	s_mov_b32 s87, 0xcccccccc
	s_mov_b32 s88, 0xaaaaaaaa
	s_mov_b32 s89, 0xaaaaaaaa
	s_mov_b32 s90, 0xf0f0f0f0
	s_mov_b32 s91, 0xf0f0f0f0
	s_lshl_b32 vcc_lo, s3, 11
	s_add_u32 s82, s82, vcc_lo
	s_addc_u32 s83, s83, 0
	v_lshl_add_u32 v246, v237, 4, s101
	v_lshrrev_b32_e32 v247, 2, v235
	v_add_u32_e32 v247, v247, v246
	v_add_u32_e32 v247, 0x10000, v247
	s_mov_b32 s100, 0
	s_mov_b32 s98, 0
	s_mov_b32 s99, 0
	s_lshl3_add_u32 vcc_lo, s98, s99
	v_lshl_add_u32 v119, vcc_lo, 8, v236
	global_load_dwordx4 v[80:83], v119, s[82:83]
	global_load_dwordx4 v[84:87], v119, s[82:83] offset:16
	v_lshl_add_u32 v116, s98, 9, v246
	ds_read_b128 v[112:115], v116
	ds_read_b128 v[138:141], v116 offset:16
	ds_read_b128 v[250:253], v116 offset:32
	ds_read_b128 v[242:245], v116 offset:48
	v_lshl_or_b32 v240, s99, 21, v235
	s_waitcnt lgkmcnt(0)
	v_and_or_b32 v112, v112, s2, v240
	v_and_or_b32 v113, v113, s2, v240
	global_load_dwordx4 v[0:3], v112, s[80:81] sc1
	global_load_dwordx4 v[4:7], v113, s[80:81] sc1
	v_and_or_b32 v114, v114, s2, v240
	v_and_or_b32 v115, v115, s2, v240
	global_load_dwordx4 v[8:11], v114, s[80:81] sc1
	global_load_dwordx4 v[12:15], v115, s[80:81] sc1
	v_and_or_b32 v138, v138, s2, v240
	v_and_or_b32 v139, v139, s2, v240
	global_load_dwordx4 v[16:19], v138, s[80:81] sc1
	global_load_dwordx4 v[20:23], v139, s[80:81] sc1
	v_and_or_b32 v140, v140, s2, v240
	v_and_or_b32 v141, v141, s2, v240
	global_load_dwordx4 v[24:27], v140, s[80:81] sc1
	global_load_dwordx4 v[28:31], v141, s[80:81] sc1
	v_and_or_b32 v250, v250, s2, v240
	v_and_or_b32 v251, v251, s2, v240
	global_load_dwordx4 v[32:35], v250, s[80:81] sc1
	global_load_dwordx4 v[36:39], v251, s[80:81] sc1
	v_and_or_b32 v252, v252, s2, v240
	v_and_or_b32 v253, v253, s2, v240
	global_load_dwordx4 v[40:43], v252, s[80:81] sc1
	global_load_dwordx4 v[44:47], v253, s[80:81] sc1
	v_and_or_b32 v242, v242, s2, v240
	v_and_or_b32 v243, v243, s2, v240
	global_load_dwordx4 v[48:51], v242, s[80:81] sc1
	global_load_dwordx4 v[52:55], v243, s[80:81] sc1
	v_and_or_b32 v244, v244, s2, v240
	v_and_or_b32 v245, v245, s2, v240
	global_load_dwordx4 v[56:59], v244, s[80:81] sc1
	global_load_dwordx4 v[60:63], v245, s[80:81] sc1
	s_mov_b32 s92, 1
	v_lshl_add_u32 v116, s92, 9, v246
	ds_read_b128 v[112:115], v116
	ds_read_b128 v[138:141], v116 offset:16
	ds_read_b128 v[250:253], v116 offset:32
	ds_read_b128 v[242:245], v116 offset:48

.Lpg1_act:
	v_readlane_b32 s82, v232, 1
	v_readlane_b32 s83, v232, 2
	s_nop 4
	s_lshl_b32 s98, s2, 11
	s_add_u32 s98, s98, s101
	v_add_u32_e32 v116, s98, v234
	v_add_u32_e32 v117, 0x10000, v116
	ds_read_b32 v0, v116 offset:0
	ds_read_b32 v8, v117 offset:0
	ds_read_b32 v1, v116 offset:256
	ds_read_b32 v9, v117 offset:256
	ds_read_b32 v2, v116 offset:512
	ds_read_b32 v10, v117 offset:512
	ds_read_b32 v3, v116 offset:768
	ds_read_b32 v11, v117 offset:768
	ds_read_b32 v4, v116 offset:1024
	ds_read_b32 v12, v117 offset:1024
	ds_read_b32 v5, v116 offset:1280
	ds_read_b32 v13, v117 offset:1280
	ds_read_b32 v6, v116 offset:1536
	ds_read_b32 v14, v117 offset:1536
	ds_read_b32 v7, v116 offset:1792
	ds_read_b32 v15, v117 offset:1792
	s_waitcnt lgkmcnt(0)
	s_lshl_b32 s99, s2, 2
	s_add_u32 s99, s99, s33
	s_add_u32 s99, s99, 0
	s_lshl_b32 s99, s99, 9
	v_and_b32_e32 v0, 0x7f, v0
	v_lshl_add_u32 v0, v0, 2, s99
	global_load_dword v16, v0, s[82:83]
	v_and_b32_e32 v1, 0x7f, v1
	v_lshl_add_u32 v1, v1, 2, s99
	global_load_dword v17, v1, s[82:83]
	s_lshl_b32 s99, s2, 2
	s_add_u32 s99, s99, s33
	s_add_u32 s99, s99, 1
	s_lshl_b32 s99, s99, 9
	v_and_b32_e32 v2, 0x7f, v2
	v_lshl_add_u32 v2, v2, 2, s99
	global_load_dword v18, v2, s[82:83]
	v_and_b32_e32 v3, 0x7f, v3
	v_lshl_add_u32 v3, v3, 2, s99
	global_load_dword v19, v3, s[82:83]
	s_lshl_b32 s99, s2, 2
	s_add_u32 s99, s99, s33
	s_add_u32 s99, s99, 2
	s_lshl_b32 s99, s99, 9
	v_and_b32_e32 v4, 0x7f, v4
	v_lshl_add_u32 v4, v4, 2, s99
	global_load_dword v20, v4, s[82:83]
	v_and_b32_e32 v5, 0x7f, v5
	v_lshl_add_u32 v5, v5, 2, s99
	global_load_dword v21, v5, s[82:83]
	s_lshl_b32 s99, s2, 2
	s_add_u32 s99, s99, s33
	s_add_u32 s99, s99, 3
	s_lshl_b32 s99, s99, 9
	v_and_b32_e32 v6, 0x7f, v6
	v_lshl_add_u32 v6, v6, 2, s99
	global_load_dword v22, v6, s[82:83]
	v_and_b32_e32 v7, 0x7f, v7
	v_lshl_add_u32 v7, v7, 2, s99
	global_load_dword v23, v7, s[82:83]
	v_mul_f32_e32 v8, 0x3c800000, v8
	v_mul_f32_e32 v9, 0x3c800000, v9
	v_mul_f32_e32 v10, 0x3c800000, v10
	v_mul_f32_e32 v11, 0x3c800000, v11
	v_mul_f32_e32 v12, 0x3c800000, v12
	v_mul_f32_e32 v13, 0x3c800000, v13
	v_mul_f32_e32 v14, 0x3c800000, v14
	v_mul_f32_e32 v15, 0x3c800000, v15
	v_mul_f32_e32 v24, 0x3d372713, v8
	v_mul_f32_e32 v25, 0x3d372713, v9
	v_mul_f32_e32 v26, 0x3d372713, v10
	v_mul_f32_e32 v27, 0x3d372713, v11
	v_mul_f32_e32 v28, 0x3d372713, v12
	v_mul_f32_e32 v29, 0x3d372713, v13
	v_mul_f32_e32 v30, 0x3d372713, v14
	v_mul_f32_e32 v31, 0x3d372713, v15
	v_mul_f32_e32 v24, v8, v24
	v_mul_f32_e32 v25, v9, v25
	v_mul_f32_e32 v26, v10, v26
	v_mul_f32_e32 v27, v11, v27
	v_mul_f32_e32 v28, v12, v28
	v_mul_f32_e32 v29, v13, v29
	v_mul_f32_e32 v30, v14, v30
	v_mul_f32_e32 v31, v15, v31
	v_fma_f32 v24, v8, v24, v8
	v_fma_f32 v25, v9, v25, v9
	v_fma_f32 v26, v10, v26, v10
	v_fma_f32 v27, v11, v27, v11
	v_fma_f32 v28, v12, v28, v12
	v_fma_f32 v29, v13, v29, v13
	v_fma_f32 v30, v14, v30, v14
	v_fma_f32 v31, v15, v31, v15
	v_mul_f32_e32 v24, 0xbfcc422a, v24
	v_mul_f32_e32 v25, 0xbfcc422a, v25
	v_mul_f32_e32 v26, 0xbfcc422a, v26
	v_mul_f32_e32 v27, 0xbfcc422a, v27
	v_mul_f32_e32 v28, 0xbfcc422a, v28
	v_mul_f32_e32 v29, 0xbfcc422a, v29
	v_mul_f32_e32 v30, 0xbfcc422a, v30
	v_mul_f32_e32 v31, 0xbfcc422a, v31
	v_mul_f32_e32 v24, 0x3fb8aa3b, v24
	v_mul_f32_e32 v25, 0x3fb8aa3b, v25
	v_mul_f32_e32 v26, 0x3fb8aa3b, v26
	v_mul_f32_e32 v27, 0x3fb8aa3b, v27
	v_mul_f32_e32 v28, 0x3fb8aa3b, v28
	v_mul_f32_e32 v29, 0x3fb8aa3b, v29
	v_mul_f32_e32 v30, 0x3fb8aa3b, v30
	v_mul_f32_e32 v31, 0x3fb8aa3b, v31
	v_exp_f32_e32 v24, v24
	v_exp_f32_e32 v25, v25
	v_exp_f32_e32 v26, v26
	v_exp_f32_e32 v27, v27
	v_exp_f32_e32 v28, v28
	v_exp_f32_e32 v29, v29
	v_exp_f32_e32 v30, v30
	v_exp_f32_e32 v31, v31
	s_nop 0
	v_add_f32_e32 v24, 1.0, v24
	v_add_f32_e32 v25, 1.0, v25
	v_add_f32_e32 v26, 1.0, v26
	v_add_f32_e32 v27, 1.0, v27
	v_add_f32_e32 v28, 1.0, v28
	v_add_f32_e32 v29, 1.0, v29
	v_add_f32_e32 v30, 1.0, v30
	v_add_f32_e32 v31, 1.0, v31
	v_rcp_f32_e32 v24, v24
	v_rcp_f32_e32 v25, v25
	v_rcp_f32_e32 v26, v26
	v_rcp_f32_e32 v27, v27
	v_rcp_f32_e32 v28, v28
	v_rcp_f32_e32 v29, v29
	v_rcp_f32_e32 v30, v30
	v_rcp_f32_e32 v31, v31
	s_nop 0
	v_mul_f32_e32 v24, v8, v24
	v_mul_f32_e32 v25, v9, v25
	v_mul_f32_e32 v26, v10, v26
	v_mul_f32_e32 v27, v11, v27
	v_mul_f32_e32 v28, v12, v28
	v_mul_f32_e32 v29, v13, v29
	v_mul_f32_e32 v30, v14, v30
	v_mul_f32_e32 v31, v15, v31
	s_waitcnt vmcnt(0)
	v_mul_f32_e32 v24, v24, v16
	ds_write_b32 v117, v24 offset:0
	v_mul_f32_e32 v25, v25, v17
	ds_write_b32 v117, v25 offset:256
	v_mul_f32_e32 v26, v26, v18
	ds_write_b32 v117, v26 offset:512
	v_mul_f32_e32 v27, v27, v19
	ds_write_b32 v117, v27 offset:768
	v_mul_f32_e32 v28, v28, v20
	ds_write_b32 v117, v28 offset:1024
	v_mul_f32_e32 v29, v29, v21
	ds_write_b32 v117, v29 offset:1280
	v_mul_f32_e32 v30, v30, v22
	ds_write_b32 v117, v30 offset:1536
	v_mul_f32_e32 v31, v31, v23
	ds_write_b32 v117, v31 offset:1792
	s_add_u32 s2, s2, 1
	s_cmp_lt_u32 s2, 4
	s_cbranch_scc1 .Lpg1_act
; #define PG_ISSUE(BUF, TAB, e0_) do { const int isrc_ = ((e0_) < 64) ? myi0 : myi1; \
;       _Pragma("unroll") for (int e = 0; e < 8; ++e) { const int idx_ = __builtin_amdgcn_readlane(isrc_, ((e0_) + e) & 63); \
;         BUF[e] = *(const u32x4*)((TAB) + (size_t)idx_ * 1024 + lane * 16); } } while (0)
; DEV void peer_gather(const Params& P, int l, int m0, const int* idxs, const float* gs) {
;     ...
;     PG_ISSUE(b0, U, 0);
; #pragma nounroll
;     for (int e0 = 0; e0 < 128; e0 += 16) {
;       PG_ISSUE(b1, U, e0 + 8);
;       PG_U8(b0, 0, e0);
;       if (e0 + 16 < 128) PG_ISSUE(b0, U, e0 + 16); else PG_ISSUE(b0, V, 0);
;       PG_U8(b1, 0, e0 + 8);
;     }
;     float* hrow = P.out + tok * DM + lane * 16;
;     f32x4 hv[4];
; #pragma unroll
;     for (int q = 0; q < 4; ++q) hv[q] = *(const f32x4*)(hrow + 4 * q);
;     if (i + 1 < 16) {
;       const int tn = tt + 1;
;       nxa = *(const u32x4*)(hn + (size_t)(m0 + tn) * DM + lane * 16); nxb = *(const u32x4*)(hn + (size_t)(m0 + tn) * DM + lane * 16 + 8);
;       ni0 = idxs[tn * 128 + lane]; ni1 = idxs[tn * 128 + 64 + lane]; ng0 = gs[tn * 128 + lane]; ng1 = gs[tn * 128 + 64 + lane];
;     }
; #pragma nounroll
;     for (int e0 = 0; e0 < 128; e0 += 16) {
;       PG_ISSUE(b1, V, e0 + 8);
;       if (e0 == 64 && i + 1 < 16) sort_lists(lane, ni0, ni1, ng0, ng1);
;       PG_V16(b0, e0);
;       if (e0 + 16 < 128) PG_ISSUE(b0, V, e0 + 16);
;       PG_V16(b1, e0 + 8);
	s_waitcnt lgkmcnt(0)
	v_readfirstlane_b32 s80, v128
	v_readfirstlane_b32 s81, v129
	s_nop 4
	v_readfirstlane_b32 s82, v132
	v_readfirstlane_b32 s83, v133
	s_nop 4
	s_mov_b32 s2, 0xffffff80
	s_lshl_b32 vcc_lo, s3, 12
	s_add_u32 s82, s82, vcc_lo
	s_addc_u32 s83, s83, 0
	s_mov_b32 s88, 0xff00ff00
	s_mov_b32 s89, 0xff00ff00
	v_lshl_add_u32 v246, v237, 4, s101
	v_add_u32_e32 v247, 0x10000, v246
	v_lshlrev_b32_e32 v238, 2, v235
	v_bfe_u32 v116, v233, 5, 1
	v_lshl_add_u32 v238, v116, 3, v238
	v_bfe_u32 v116, v233, 4, 1
	v_lshl_add_u32 v238, v116, 4, v238
	v_bfe_u32 v116, v233, 3, 1
	v_lshl_add_u32 v238, v116, 5, v238
	s_mov_b32 s100, 0
	s_mov_b32 s98, 0
	s_mov_b32 s99, 0
	v_lshl_add_u32 v116, s98, 9, v246
	ds_read_b128 v[112:115], v116
	ds_read_b128 v[138:141], v116 offset:16
	ds_read_b128 v[250:253], v116 offset:32
	ds_read_b128 v[242:245], v116 offset:48
	v_lshl_or_b32 v240, s99, 21, v235
	s_waitcnt lgkmcnt(0)
	v_and_or_b32 v112, v112, s2, v240
	v_and_or_b32 v113, v113, s2, v240
	global_load_dwordx4 v[0:3], v112, s[80:81] sc1
	global_load_dwordx4 v[4:7], v113, s[80:81] sc1
	v_and_or_b32 v114, v114, s2, v240
	v_and_or_b32 v115, v115, s2, v240
	global_load_dwordx4 v[8:11], v114, s[80:81] sc1
	global_load_dwordx4 v[12:15], v115, s[80:81] sc1
	v_and_or_b32 v138, v138, s2, v240
	v_and_or_b32 v139, v139, s2, v240
	global_load_dwordx4 v[16:19], v138, s[80:81] sc1
	global_load_dwordx4 v[20:23], v139, s[80:81] sc1
	v_and_or_b32 v140, v140, s2, v240
	v_and_or_b32 v141, v141, s2, v240
	global_load_dwordx4 v[24:27], v140, s[80:81] sc1
	global_load_dwordx4 v[28:31], v141, s[80:81] sc1
	v_and_or_b32 v250, v250, s2, v240
	v_and_or_b32 v251, v251, s2, v240
	global_load_dwordx4 v[32:35], v250, s[80:81] sc1
	global_load_dwordx4 v[36:39], v251, s[80:81] sc1
	v_and_or_b32 v252, v252, s2, v240
	v_and_or_b32 v253, v253, s2, v240
	global_load_dwordx4 v[40:43], v252, s[80:81] sc1
	global_load_dwordx4 v[44:47], v253, s[80:81] sc1
	v_and_or_b32 v242, v242, s2, v240
	v_and_or_b32 v243, v243, s2, v240
	global_load_dwordx4 v[48:51], v242, s[80:81] sc1
	global_load_dwordx4 v[52:55], v243, s[80:81] sc1
	v_and_or_b32 v244, v244, s2, v240
	v_and_or_b32 v245, v245, s2, v240
	global_load_dwordx4 v[56:59], v244, s[80:81] sc1
	global_load_dwordx4 v[60:63], v245, s[80:81] sc1
	s_mov_b32 s92, 1
	v_lshl_add_u32 v116, s92, 9, v246
	ds_read_b128 v[112:115], v116
	ds_read_b128 v[138:141], v116 offset:16
	ds_read_b128 v[250:253], v116 offset:32
	ds_read_b128 v[242:245], v116 offset:48
	v_lshl_add_u32 v117, s98, 9, v247
	ds_read_b128 v[84:87], v117
	ds_read_b128 v[88:91], v117 offset:16
	ds_read_b128 v[92:95], v117 offset:32
	ds_read_b128 v[96:99], v117 offset:48
	s_waitcnt vmcnt(0)
